# attention: K-tile rows read in permuted order so V fragments are single conflict-free ds_read_b128 (was 2 b64, 2-way conflict)
# speedup vs baseline: 1.0815x; 1.0039x over previous
; DI void attn_item(const Params& p, char* smem, u16* qbase, const u16* gabase, const u16* kbase, const u16* vtbase,
;                   int tkv, int nkt, int mylimit, const float* lam_p, const int g_wave) {
;     ...
;         float4 sl = *(const float4*)(p.subln + dv);
; DI void phase2(const Params& p, char* smem, const int g_wave) {
;     ...
;       const size_t rowq = prm ? (size_t)b * 8192 + qb * 256 : (size_t)TP + b * 64;
;       u16* qbase = (u16*)(p.ws + WS_Q) + rowq * 1024 + h * 128;
;       const u16* gabase = (const u16*)(p.out + O_Y) + rowq * 1024 + h * 128;
;       const u16* kbase = prm ? (const u16*)(p.ws + WS_K) + (size_t)b * 8192 * 1024 + h * 128 : (const u16*)(p.ws + WS_KC) + (size_t)b * 1088 * 1024 + h * 128;
;       const u16* vtbase = prm ? (const u16*)(p.ws + WS_VT) + (size_t)bh * 128 * 8192 : (const u16*)(p.ws + WS_VTS) + (size_t)bh * 128 * 1088;
;       const int tkv = prm ? 8192 : 1088, nkt = prm ? 4 * (qb + 1) : 17;
;       const int mylimit = prm ? 4 * qb + (wid >> 1) + 1 : (wid < 2 ? 17 : 0);
.LBB0_679:
	s_or_b64 exec, exec, s[0:1]
	s_and_b32 s0, s75, 0xffffffc0
	s_cmpk_lt_u32 s75, 0x80
	s_cselect_b32 s2, 17, 0
	s_lshr_b32 s28, s75, 7
	s_add_i32 s28, s28, 1
	s_cmpk_gt_u32 s75, 0xff
	s_cselect_b64 s[8:9], -1, 0
	s_lshl_b32 s29, s3, 3
	v_or_b32_e32 v196, s0, v2
	s_movk_i32 s6, 0x80
	v_cmp_gt_u32_e64 s[10:11], s6, v196
	s_and_saveexec_b64 s[4:5], s[10:11]
	v_lshlrev_b32_e32 v6, 2, v196
	global_load_dword v7, v6, s[44:45]
	v_add_u32_e32 v6, 0x25100, v6
	s_waitcnt vmcnt(0)
	ds_write_b32 v6, v7
	s_or_b64 exec, exec, s[4:5]
	s_sub_i32 s30, s29, 32
	s_lshl_b32 s0, s3, 4
	s_add_u32 s33, s72, 0x9641000
	s_addc_u32 s75, s73, 0
	v_writelane_b32 v255, s0, 9
	s_add_u32 s0, s72, 0x19741000
	v_writelane_b32 v255, s0, 17
	s_addc_u32 s0, s73, 0
	v_writelane_b32 v255, s0, 19
	s_add_u32 s0, s72, 0x11741000
	v_writelane_b32 v255, s0, 21
	s_addc_u32 s0, s73, 0
	v_writelane_b32 v255, s0, 23
	s_add_u32 s0, s72, 0x22841000
	v_writelane_b32 v255, s0, 10
	s_addc_u32 s0, s73, 0
	v_writelane_b32 v255, s0, 15
	s_add_u32 s0, s72, 0x1a841000
	v_writelane_b32 v255, s0, 11
	s_addc_u32 s0, s73, 0
	s_add_u32 s10, s72, 0x23941000
	s_addc_u32 s11, s73, 0
	v_writelane_b32 v255, s0, 13
	s_add_u32 s0, s70, 0x8100000
	s_addc_u32 s95, s71, 0
	s_add_u32 s16, s72, 0x239a3700
	s_addc_u32 s17, s73, 0
	s_add_u32 s18, s72, 0x239a5000
	v_writelane_b32 v255, s0, 12
	s_addc_u32 s19, s73, 0
	s_lshl_b32 s0, s3, 6
	s_add_i32 s96, s0, 16
	s_add_i32 s96, s96, 0xa100
	v_mov_b32_e32 v3, 0
	s_mov_b64 s[24:25], 0x80
	s_mov_b64 s[26:27], 0x20000
	s_mov_b32 s97, 0x3e38aa3b
	s_mov_b32 s3, 1.0
	s_mov_b32 s98, 0x800000
	s_add_i32 s99, 16, 0x1e700
	s_add_i32 s36, 16, 0x1f800
	s_movk_i32 s37, 0x90
	s_add_i32 s31, 16, 0x1ec00
	s_movk_i32 s86, 0x1900
	s_movk_i32 s87, 0x1000
	s_add_i32 s88, 16, 0x1c300
	s_movk_i32 s89, 0x7fff
	s_mov_b32 s90, 0x7060302
	s_add_i32 s91, 16, 0x1d500
	v_mov_b32_e32 v197, 0x3a27c5ac
	s_add_i32 s92, 16, 0x1a180
	s_add_i32 s93, 16, 0x18180
	s_add_i32 s94, 16, 0x100
	v_mov_b32_e32 v183, 1.0
	s_branch .LBB0_683

; DI void attn_item(const Params& p, char* smem, u16* qbase, const u16* gabase, const u16* kbase, const u16* vtbase,
;                   int tkv, int nkt, int mylimit, const float* lam_p, const int g_wave) {
;     ...
;   unsigned kso[2], vso[2];
; #pragma unroll
;   for (int i = 0; i < 2; ++i) {
;     const int krow = 4 * (2 * wid + i) + (lane >> 4), kpos = lane & 15;
;     kso[i] = (unsigned)(krow * 1024 + ((kpos ^ (krow & 15)) * 8)) * 2u;
;     const int vrow = 8 * (2 * wid + i) + (lane >> 3), vpos = lane & 7;
;     vso[i] = (unsigned)(vrow * tkv + ((vpos ^ ((vrow >> 1) & 7)) * 8)) * 2u;
;   }
;     ...
;   f32x16 O0[4], O1[4];
; #pragma unroll
;   for (int d = 0; d < 4; ++d) { O0[d] = f32x16{}; O1[d] = f32x16{}; }
;   float l0 = 0.f, l1 = 0.f, m0 = -1e30f, m1 = -1e30f;
;     ...
;   STAGE_KV(0, 0);
;   asm volatile("s_waitcnt vmcnt(0)" ::: "memory");
;   __syncthreads();
; #pragma unroll 1
;   for (int kt = 0; kt < nkt; ++kt) {
;     if (kt + 1 < nkt) STAGE_KV((kt + 1) & 1, kt + 1);
;     if (kt < mylimit) {
;       const char* Kt = Kb + (kt & 1) * KBUF;
;       const char* Vt = Vb + (kt & 1) * VBUF;
;       int zq = 0, kz = (r & 15) * 16, vz = ((r >> 1) & 7) * 16;
;       asm volatile("" : "+v"(zq), "+v"(kz), "+v"(vz));
;       const char* Qk = Qs + zq;
.LBB0_708:
	s_lshl_b64 s[42:43], s[42:43], 10
	s_add_i32 s82, s82, 4
	s_and_b64 s[34:35], s[54:55], exec
	s_cselect_b32 s34, s82, 17
	s_add_u32 s54, s66, s51
	v_lshrrev_b32_e32 v6, 3, v2
	s_addc_u32 s55, s67, 0
	s_lshl_b32 s35, s80, 1
	v_lshl_add_u32 v7, s80, 3, v5
	v_lshl_or_b32 v9, s80, 4, v6
	v_xor_b32_e32 v11, v5, v4
	v_xor_b32_e32 v8, v7, v4
	v_mul_lo_u32 v10, v9, s79
	v_lshlrev_b32_e32 v11, 3, v11
	s_or_b32 s35, s35, 1
	v_lshlrev_b32_e32 v8, 4, v8
	v_and_or_b32 v10, v11, 56, v10
	v_lshl_add_u32 v11, s35, 2, v5
	v_lshl_or_b32 v6, s35, 3, v6
	s_lshl_b32 s35, s80, 11
	v_and_b32_e32 v8, 0xf0, v8
	v_xor_b32_e32 v12, v11, v4
	v_mul_lo_u32 v13, v6, s79
	v_lshrrev_b32_e32 v6, 1, v6
	s_add_i32 s35, s35, 16
	v_lshl_or_b32 v7, v7, 11, v8
	v_lshlrev_b32_e32 v12, 4, v12
	v_xor_b32_e32 v14, v6, v4
	s_mov_b32 m0, s35
	v_lshlrev_b32_e32 v10, 1, v10
	v_and_b32_e32 v12, 0xf0, v12
	v_lshlrev_b32_e32 v14, 3, v14
	global_load_lds_dwordx4 v7, s[54:55]
	s_add_i32 m0, s35, 0x8000
	v_lshl_or_b32 v11, v11, 11, v12
	v_and_or_b32 v13, v14, 56, v13
	global_load_lds_dwordx4 v10, s[76:77]
	s_add_i32 m0, s35, 0x400
	v_lshlrev_b32_e32 v13, 1, v13
	global_load_lds_dwordx4 v11, s[54:55]
	s_add_i32 m0, s35, 0x8400
	v_and_b32_e32 v7, 31, v4
	global_load_lds_dwordx4 v13, s[76:77]
	v_lshlrev_b32_e32 v10, 3, v4
	v_and_b32_e32 v182, 0x70, v10
	v_mul_u32_u24_e32 v10, 0x110, v7
	v_lshlrev_b32_e32 v7, 7, v7
	s_add_u32 s54, s76, 0x80
	v_lshrrev_b32_e32 v2, 5, v2
	v_add_u32_e32 v11, 16, v7
	s_addc_u32 s55, s77, 0
	s_lshl_b32 s76, s79, 1
	v_lshlrev_b32_e32 v185, 4, v2
	v_add_u32_e32 v198, v11, v7
	v_lshl_add_u32 v206, v2, 3, v11
	v_mul_lo_u32 v2, s76, v9
	v_bitop3_b32 v7, v5, 7, v4 bitop3:0x48
	v_lshl_add_u32 v2, v7, 4, v2
	v_lshl_add_u64 v[188:189], s[54:55], 0, v[2:3]
	v_or_b32_e32 v2, 8, v9
	s_and_b32 s50, s50, 7
	v_mul_lo_u32 v2, s76, v2
	v_bitop3_b32 v4, v6, 7, v4 bitop3:0x48
	s_lshl_b32 s50, s50, 8
	v_lshl_add_u32 v2, v4, 4, v2
	s_add_u32 s50, s66, s50
	v_lshl_add_u64 v[190:191], s[54:55], 0, v[2:3]
	v_lshlrev_b32_e32 v2, 11, v5
	s_addc_u32 s55, s67, 0
	v_lshl_add_u32 v4, s80, 14, v2
	s_add_u32 s54, s50, 0x20000
	v_or_b32_e32 v2, v4, v8
	s_addc_u32 s55, s55, 0
	v_lshl_add_u64 v[192:193], s[54:55], 0, v[2:3]
	v_or_b32_e32 v2, v4, v12
	s_waitcnt vmcnt(0)
	v_add_u32_e32 v2, 0x2000, v2
	v_mov_b32_e32 v16, v3
	v_mov_b32_e32 v17, v3
	v_add3_u32 v205, s81, v10, v185
	v_lshl_add_u64 v[194:195], s[54:55], 0, v[2:3]
	v_mov_b32_e32 v2, v3
	v_mov_b32_e32 v4, v3
	v_mov_b32_e32 v5, v3
	v_mov_b32_e32 v6, v3
	v_mov_b32_e32 v7, v3
	v_mov_b32_e32 v8, v3
	v_mov_b32_e32 v9, v3
	v_mov_b32_e32 v10, v3
	v_mov_b32_e32 v11, v3
	v_mov_b32_e32 v12, v3
	v_mov_b32_e32 v13, v3
	v_mov_b32_e32 v14, v3
	v_mov_b32_e32 v15, v3
	v_mov_b64_e32 v[128:129], v[16:17]
	v_mov_b64_e32 v[96:97], v[16:17]
	v_mov_b64_e32 v[64:65], v[16:17]
	v_mov_b64_e32 v[32:33], v[16:17]
	v_mov_b64_e32 v[144:145], v[16:17]
	v_mov_b64_e32 v[112:113], v[16:17]
	v_mov_b64_e32 v[80:81], v[16:17]
	v_mov_b64_e32 v[48:49], v[16:17]
	v_xor_b32_e32 v199, v184, v185
	s_mov_b32 s50, 0
	v_mov_b32_e32 v207, 0xf149f2ca
	v_mov_b32_e32 v186, 0
	v_mov_b64_e32 v[126:127], v[14:15]
	v_mov_b64_e32 v[124:125], v[12:13]
	v_mov_b64_e32 v[122:123], v[10:11]
	v_mov_b64_e32 v[120:121], v[8:9]
	v_mov_b64_e32 v[118:119], v[6:7]
	v_mov_b64_e32 v[116:117], v[4:5]
	v_mov_b64_e32 v[114:115], v[2:3]
	v_mov_b64_e32 v[94:95], v[14:15]
	v_mov_b64_e32 v[92:93], v[12:13]
	v_mov_b64_e32 v[90:91], v[10:11]
	v_mov_b64_e32 v[88:89], v[8:9]
	v_mov_b64_e32 v[86:87], v[6:7]
	v_mov_b64_e32 v[84:85], v[4:5]
	v_mov_b64_e32 v[82:83], v[2:3]
	v_mov_b64_e32 v[62:63], v[14:15]
	v_mov_b64_e32 v[60:61], v[12:13]
	v_mov_b64_e32 v[58:59], v[10:11]
	v_mov_b64_e32 v[56:57], v[8:9]
	v_mov_b64_e32 v[54:55], v[6:7]
	v_mov_b64_e32 v[52:53], v[4:5]
	v_mov_b64_e32 v[50:51], v[2:3]
	v_mov_b64_e32 v[30:31], v[14:15]
	v_mov_b64_e32 v[28:29], v[12:13]
	v_mov_b64_e32 v[26:27], v[10:11]
	v_mov_b64_e32 v[24:25], v[8:9]
	v_mov_b64_e32 v[22:23], v[6:7]
	v_mov_b64_e32 v[20:21], v[4:5]
	v_mov_b64_e32 v[18:19], v[2:3]
	v_mov_b64_e32 v[142:143], v[14:15]
	v_mov_b64_e32 v[140:141], v[12:13]
	v_mov_b64_e32 v[138:139], v[10:11]
	v_mov_b64_e32 v[136:137], v[8:9]
	v_mov_b64_e32 v[134:135], v[6:7]
	v_mov_b64_e32 v[132:133], v[4:5]
	v_mov_b64_e32 v[130:131], v[2:3]
	v_mov_b64_e32 v[110:111], v[14:15]
	v_mov_b64_e32 v[108:109], v[12:13]
	v_mov_b64_e32 v[106:107], v[10:11]
	v_mov_b64_e32 v[104:105], v[8:9]
	v_mov_b64_e32 v[102:103], v[6:7]
	v_mov_b64_e32 v[100:101], v[4:5]
	v_mov_b64_e32 v[98:99], v[2:3]
	v_mov_b64_e32 v[78:79], v[14:15]
	v_mov_b64_e32 v[76:77], v[12:13]
	v_mov_b64_e32 v[74:75], v[10:11]
	v_mov_b64_e32 v[72:73], v[8:9]
	v_mov_b64_e32 v[70:71], v[6:7]
	v_mov_b64_e32 v[68:69], v[4:5]
	v_mov_b64_e32 v[66:67], v[2:3]
	v_mov_b64_e32 v[46:47], v[14:15]
	v_mov_b64_e32 v[44:45], v[12:13]
	v_mov_b64_e32 v[42:43], v[10:11]
	v_mov_b64_e32 v[40:41], v[8:9]
	v_mov_b64_e32 v[38:39], v[6:7]
	v_mov_b64_e32 v[36:37], v[4:5]
	v_mov_b64_e32 v[34:35], v[2:3]
	v_mov_b32_e32 v187, 0
	v_mov_b32_e32 v2, 0xf149f2ca
	s_mov_b32 s55, 0
	v_and_b32_e32 v216, 31, v196
	v_and_b32_e32 v217, 4, v216
	v_and_b32_e32 v252, 8, v216
	v_lshlrev_b32_e32 v217, 1, v217
	v_lshrrev_b32_e32 v252, 1, v252
	v_and_b32_e32 v253, 0x13, v216
	v_or3_b32 v253, v253, v217, v252
	v_lshl_add_u32 v198, v253, 8, 16
	v_and_b32_e32 v184, 15, v253
	v_lshlrev_b32_e32 v184, 4, v184
	v_xor_b32_e32 v199, v184, v185
	v_lshl_add_u32 v206, v216, 7, 16
	v_xor_b32_e32 v182, v182, v185
	s_movk_i32 s79, 0x60
	s_movk_i32 s80, 0x80
	s_movk_i32 s81, 0xa0
	s_movk_i32 s82, 0xc0
	s_movk_i32 s83, 0xe0
	s_movk_i32 s32, 0x50
	s_movk_i32 s85, 0x70
	s_waitcnt vmcnt(0) lgkmcnt(0)
	s_barrier
	s_add_i32 s54, s55, 1
	s_cmp_ge_u32 s54, s34
	s_cbranch_scc1 .LBB0_711
	s_branch .LBB0_710

; DI void attn_item(const Params& p, char* smem, u16* qbase, const u16* gabase, const u16* kbase, const u16* vtbase,
;                   int tkv, int nkt, int mylimit, const float* lam_p, const int g_wave) {
;     ...
; #pragma unroll
;       for (int d = 0; d < 4; ++d) {
;         const int vrow = 32 * d + r;
; #pragma unroll
;         for (int sp = 0; sp < 4; ++sp) {
;           const u32x2 lo = *(const u32x2*)(Vt + vrow * 128 + ((32 * sp) ^ vz) + 8 * hh);
;           const u32x2 hi = *(const u32x2*)(Vt + vrow * 128 + ((32 * sp + 16) ^ vz) + 8 * hh);
;           u32x4 w = {lo[0], lo[1], hi[0], hi[1]};
;           const bf16x8 vf = *reinterpret_cast<bf16x8*>(&w);
;           O0[d] = __builtin_amdgcn_mfma_f32_32x32x16_bf16(vf, pf0[sp], O0[d], 0, 0, 0);
;           O1[d] = __builtin_amdgcn_mfma_f32_32x32x16_bf16(vf, pf1[sp], O1[d], 0, 0, 0);
;         }
.Lat_nr0:
	v_fma_f32 v162, v162, s97, -v207
	v_fma_f32 v163, v163, s97, -v207
	v_fma_f32 v164, v164, s97, -v207
	v_fma_f32 v165, v165, s97, -v207
	v_fma_f32 v166, v166, s97, -v207
	v_fma_f32 v167, v167, s97, -v207
	v_fma_f32 v168, v168, s97, -v207
	v_fma_f32 v169, v169, s97, -v207
	v_exp_f32_e32 v162, v162
	v_exp_f32_e32 v163, v163
	v_exp_f32_e32 v164, v164
	v_exp_f32_e32 v165, v165
	v_exp_f32_e32 v166, v166
	v_exp_f32_e32 v167, v167
	v_exp_f32_e32 v168, v168
	v_exp_f32_e32 v169, v169
	s_waitcnt lgkmcnt(0)
	v_mfma_f32_32x32x16_bf16 v[220:235], v[200:203], v[212:215], v[220:235]
	v_mfma_f32_32x32x16_bf16 v[236:251], v[208:211], v[212:215], v[236:251]
	v_xad_u32 v252, v199, s82, v16
	ds_read_b128 v[200:203], v252
	ds_read_b128 v[208:211], v252 offset:8192
	ds_read_b128 v[212:215], v205 offset:192
	v_fma_f32 v170, v170, s97, -v207
	v_fma_f32 v171, v171, s97, -v207
	v_fma_f32 v172, v172, s97, -v207
	v_fma_f32 v173, v173, s97, -v207
	v_fma_f32 v174, v174, s97, -v207
	v_fma_f32 v175, v175, s97, -v207
	v_fma_f32 v176, v176, s97, -v207
	v_fma_f32 v177, v177, s97, -v207
	v_cvt_pk_bf16_f32 v178, v162, v163
	v_cvt_pk_bf16_f32 v179, v164, v165
	v_cvt_pk_bf16_f32 v180, v166, v167
	v_cvt_pk_bf16_f32 v181, v168, v169
	v_exp_f32_e32 v170, v170
	v_exp_f32_e32 v171, v171
	v_exp_f32_e32 v172, v172
	v_exp_f32_e32 v173, v173
	v_exp_f32_e32 v174, v174
	v_exp_f32_e32 v175, v175
	v_exp_f32_e32 v176, v176
	v_exp_f32_e32 v177, v177
	v_mov_b32_e32 v17, v162
	v_mov_b32_e32 v219, v163
	v_add_f32_e32 v17, v164, v17
	v_add_f32_e32 v219, v165, v219
	v_add_f32_e32 v17, v166, v17
	v_add_f32_e32 v219, v167, v219
	v_add_f32_e32 v17, v168, v17
	v_add_f32_e32 v219, v169, v219
	s_waitcnt lgkmcnt(0)
	v_mfma_f32_32x32x16_bf16 v[220:235], v[200:203], v[212:215], v[220:235]
	v_mfma_f32_32x32x16_bf16 v[236:251], v[208:211], v[212:215], v[236:251]
	v_xad_u32 v253, v199, s83, v16
	ds_read_b128 v[200:203], v253
	ds_read_b128 v[208:211], v253 offset:8192
	ds_read_b128 v[212:215], v205 offset:224
	v_fma_f32 v146, v146, s97, -v207
	v_fma_f32 v147, v147, s97, -v207
	v_fma_f32 v148, v148, s97, -v207
	v_fma_f32 v149, v149, s97, -v207
	v_fma_f32 v150, v150, s97, -v207
	v_fma_f32 v151, v151, s97, -v207
	v_fma_f32 v152, v152, s97, -v207
	v_fma_f32 v153, v153, s97, -v207
	v_cvt_pk_bf16_f32 v12, v170, v171
	v_cvt_pk_bf16_f32 v13, v172, v173
	v_cvt_pk_bf16_f32 v14, v174, v175
	v_cvt_pk_bf16_f32 v15, v176, v177
	v_exp_f32_e32 v146, v146
	v_exp_f32_e32 v147, v147
	v_exp_f32_e32 v148, v148
	v_exp_f32_e32 v149, v149
	v_exp_f32_e32 v150, v150
	v_exp_f32_e32 v151, v151
	v_exp_f32_e32 v152, v152
	v_exp_f32_e32 v153, v153
	v_add_f32_e32 v17, v170, v17
	v_add_f32_e32 v219, v171, v219
	v_add_f32_e32 v17, v172, v17
	v_add_f32_e32 v219, v173, v219
	v_add_f32_e32 v17, v174, v17
	v_add_f32_e32 v219, v175, v219
	v_add_f32_e32 v17, v176, v17
	v_add_f32_e32 v219, v177, v219
	s_waitcnt lgkmcnt(0)
	v_mfma_f32_32x32x16_bf16 v[220:235], v[200:203], v[212:215], v[220:235]
	v_mfma_f32_32x32x16_bf16 v[236:251], v[208:211], v[212:215], v[236:251]
	v_fma_f32 v154, v154, s97, -v207
	v_fma_f32 v155, v155, s97, -v207
	v_fma_f32 v156, v156, s97, -v207
	v_fma_f32 v157, v157, s97, -v207
	v_fma_f32 v158, v158, s97, -v207
	v_fma_f32 v159, v159, s97, -v207
	v_fma_f32 v160, v160, s97, -v207
	v_fma_f32 v161, v161, s97, -v207
	v_cvt_pk_bf16_f32 v8, v146, v147
	v_cvt_pk_bf16_f32 v9, v148, v149
	v_cvt_pk_bf16_f32 v10, v150, v151
	v_cvt_pk_bf16_f32 v11, v152, v153
	v_exp_f32_e32 v154, v154
	v_exp_f32_e32 v155, v155
	v_exp_f32_e32 v156, v156
	v_exp_f32_e32 v157, v157
	v_exp_f32_e32 v158, v158
	v_exp_f32_e32 v159, v159
	v_exp_f32_e32 v160, v160
	v_exp_f32_e32 v161, v161
	v_add_f32_e32 v17, v146, v17
	v_add_f32_e32 v219, v147, v219
	v_add_f32_e32 v17, v148, v17
	v_add_f32_e32 v219, v149, v219
	v_add_f32_e32 v17, v150, v17
	v_add_f32_e32 v219, v151, v219
	v_add_f32_e32 v17, v152, v17
	v_add_f32_e32 v219, v153, v219
	v_cvt_pk_bf16_f32 v4, v154, v155
	v_cvt_pk_bf16_f32 v5, v156, v157
	v_cvt_pk_bf16_f32 v6, v158, v159
	v_cvt_pk_bf16_f32 v7, v160, v161
	v_add_f32_e32 v17, v154, v17
	v_add_f32_e32 v219, v155, v219
	v_add_f32_e32 v17, v156, v17
	v_add_f32_e32 v219, v157, v219
	v_add_f32_e32 v17, v158, v17
	v_add_f32_e32 v219, v159, v219
	v_add_f32_e32 v17, v160, v17
	v_add_f32_e32 v219, v161, v219
	v_add_f32_e32 v17, v17, v219
	v_add_f32_e32 v186, v186, v17
	v_add_u32_e32 v16, s55, v206
	v_add_u32_e32 v200, v182, v16
	v_xad_u32 v201, v182, 32, v16
	v_xad_u32 v202, v182, 64, v16
	v_xad_u32 v203, v182, s79, v16
	ds_read_b128 v[162:165], v200 offset:32768
	ds_read_b128 v[166:169], v200 offset:36864
	ds_read_b128 v[170:173], v200 offset:40960
	ds_read_b128 v[174:177], v200 offset:45056
	v_max3_f32 v17, v220, v221, v222
	v_max3_f32 v219, v236, v237, v238
	v_max3_f32 v17, v17, v223, v224
	v_max3_f32 v219, v219, v239, v240
	v_max3_f32 v17, v17, v225, v226
	v_max3_f32 v219, v219, v241, v242
	v_max3_f32 v17, v17, v227, v228
	v_max3_f32 v219, v219, v243, v244
	s_waitcnt lgkmcnt(3)
	v_mfma_f32_32x32x16_bf16 v[130:145], v[162:165], v[178:181], v[130:145]
	v_max3_f32 v17, v17, v229, v230
	v_max3_f32 v219, v219, v245, v246
	v_max3_f32 v17, v17, v231, v232
	v_max3_f32 v219, v219, v247, v248
	v_max3_f32 v17, v17, v233, v234
	v_max3_f32 v219, v219, v249, v250
	v_max_f32_e32 v219, v219, v251
	v_max3_f32 v17, v17, v235, v219
	s_waitcnt lgkmcnt(2)
	v_mfma_f32_32x32x16_bf16 v[98:113], v[166:169], v[178:181], v[98:113]
	v_mov_b32_e32 v219, v17
	s_nop 1
	v_permlane32_swap_b32_e32 v17, v219
	v_max_f32_e32 v17, v17, v219
	v_mul_f32_e32 v17, s97, v17
	v_add_f32_e32 v219, 0x41000000, v2
	v_cmp_le_f32_e32 vcc, v17, v219
	s_cmp_eq_u64 vcc, exec
	s_cbranch_scc1 .Lat_nr1
; DI void attn_item(const Params& p, char* smem, u16* qbase, const u16* gabase, const u16* kbase, const u16* vtbase,
;                   int tkv, int nkt, int mylimit, const float* lam_p, const int g_wave) {
;     ...
; #pragma unroll
;       for (int d = 0; d < 4; ++d) {
;         const int vrow = 32 * d + r;
; #pragma unroll
;         for (int sp = 0; sp < 4; ++sp) {
;           const u32x2 lo = *(const u32x2*)(Vt + vrow * 128 + ((32 * sp) ^ vz) + 8 * hh);
;           const u32x2 hi = *(const u32x2*)(Vt + vrow * 128 + ((32 * sp + 16) ^ vz) + 8 * hh);
;           u32x4 w = {lo[0], lo[1], hi[0], hi[1]};
;           const bf16x8 vf = *reinterpret_cast<bf16x8*>(&w);
;           O0[d] = __builtin_amdgcn_mfma_f32_32x32x16_bf16(vf, pf0[sp], O0[d], 0, 0, 0);
;           O1[d] = __builtin_amdgcn_mfma_f32_32x32x16_bf16(vf, pf1[sp], O1[d], 0, 0, 0);
;         }
	v_max_f32_e32 v219, v2, v17
	v_sub_f32_e32 v216, v2, v219
	v_exp_f32_e32 v216, v216
	v_mov_b32_e32 v2, v219
	s_nop 0
	v_pk_mul_f32 v[128:129], v[128:129], v[216:217] op_sel_hi:[1,0]
	v_pk_mul_f32 v[126:127], v[126:127], v[216:217] op_sel_hi:[1,0]
	v_pk_mul_f32 v[124:125], v[124:125], v[216:217] op_sel_hi:[1,0]
	v_pk_mul_f32 v[122:123], v[122:123], v[216:217] op_sel_hi:[1,0]
	v_pk_mul_f32 v[120:121], v[120:121], v[216:217] op_sel_hi:[1,0]
	v_pk_mul_f32 v[118:119], v[118:119], v[216:217] op_sel_hi:[1,0]
	v_pk_mul_f32 v[116:117], v[116:117], v[216:217] op_sel_hi:[1,0]
	v_pk_mul_f32 v[114:115], v[114:115], v[216:217] op_sel_hi:[1,0]
	v_pk_mul_f32 v[96:97], v[96:97], v[216:217] op_sel_hi:[1,0]
	v_pk_mul_f32 v[94:95], v[94:95], v[216:217] op_sel_hi:[1,0]
	v_pk_mul_f32 v[92:93], v[92:93], v[216:217] op_sel_hi:[1,0]
	v_pk_mul_f32 v[90:91], v[90:91], v[216:217] op_sel_hi:[1,0]
	v_pk_mul_f32 v[88:89], v[88:89], v[216:217] op_sel_hi:[1,0]
	v_pk_mul_f32 v[86:87], v[86:87], v[216:217] op_sel_hi:[1,0]
	v_pk_mul_f32 v[84:85], v[84:85], v[216:217] op_sel_hi:[1,0]
	v_pk_mul_f32 v[82:83], v[82:83], v[216:217] op_sel_hi:[1,0]
	v_pk_mul_f32 v[64:65], v[64:65], v[216:217] op_sel_hi:[1,0]
	v_pk_mul_f32 v[62:63], v[62:63], v[216:217] op_sel_hi:[1,0]
	v_pk_mul_f32 v[60:61], v[60:61], v[216:217] op_sel_hi:[1,0]
	v_pk_mul_f32 v[58:59], v[58:59], v[216:217] op_sel_hi:[1,0]
	v_pk_mul_f32 v[56:57], v[56:57], v[216:217] op_sel_hi:[1,0]
	v_pk_mul_f32 v[54:55], v[54:55], v[216:217] op_sel_hi:[1,0]
	v_pk_mul_f32 v[52:53], v[52:53], v[216:217] op_sel_hi:[1,0]
	v_pk_mul_f32 v[50:51], v[50:51], v[216:217] op_sel_hi:[1,0]
	v_pk_mul_f32 v[32:33], v[32:33], v[216:217] op_sel_hi:[1,0]
	v_pk_mul_f32 v[30:31], v[30:31], v[216:217] op_sel_hi:[1,0]
	v_pk_mul_f32 v[28:29], v[28:29], v[216:217] op_sel_hi:[1,0]
	v_pk_mul_f32 v[26:27], v[26:27], v[216:217] op_sel_hi:[1,0]
	v_pk_mul_f32 v[24:25], v[24:25], v[216:217] op_sel_hi:[1,0]
	v_pk_mul_f32 v[22:23], v[22:23], v[216:217] op_sel_hi:[1,0]
	v_pk_mul_f32 v[20:21], v[20:21], v[216:217] op_sel_hi:[1,0]
	v_pk_mul_f32 v[18:19], v[18:19], v[216:217] op_sel_hi:[1,0]
	v_mul_f32_e32 v187, v187, v216
.Lat_nr1:
	s_waitcnt lgkmcnt(1)
	v_mfma_f32_32x32x16_bf16 v[66:81], v[170:173], v[178:181], v[66:81]
	v_fma_f32 v220, v220, s97, -v2
	v_fma_f32 v221, v221, s97, -v2
	v_fma_f32 v222, v222, s97, -v2
	v_fma_f32 v223, v223, s97, -v2
	v_fma_f32 v224, v224, s97, -v2
	v_fma_f32 v225, v225, s97, -v2
	v_fma_f32 v226, v226, s97, -v2
	v_fma_f32 v227, v227, s97, -v2
	s_waitcnt lgkmcnt(0)
	v_mfma_f32_32x32x16_bf16 v[34:49], v[174:177], v[178:181], v[34:49]
	v_exp_f32_e32 v220, v220
	v_exp_f32_e32 v221, v221
	v_exp_f32_e32 v222, v222
	v_exp_f32_e32 v223, v223
	v_exp_f32_e32 v224, v224
	v_exp_f32_e32 v225, v225
	v_exp_f32_e32 v226, v226
	v_exp_f32_e32 v227, v227
	v_fma_f32 v228, v228, s97, -v2
	v_fma_f32 v229, v229, s97, -v2
	v_fma_f32 v230, v230, s97, -v2
	v_fma_f32 v231, v231, s97, -v2
	v_fma_f32 v232, v232, s97, -v2
	v_fma_f32 v233, v233, s97, -v2
	v_fma_f32 v234, v234, s97, -v2
	v_fma_f32 v235, v235, s97, -v2
	v_cvt_pk_bf16_f32 v146, v220, v221
	v_cvt_pk_bf16_f32 v147, v222, v223
	v_cvt_pk_bf16_f32 v148, v224, v225
	v_cvt_pk_bf16_f32 v149, v226, v227
	s_nop 1
	v_mfma_f32_32x32x16_bf16 v[114:129], v[162:165], v[146:149], v[114:129]
	ds_read_b128 v[162:165], v201 offset:32768
	v_exp_f32_e32 v228, v228
	v_exp_f32_e32 v229, v229
	v_exp_f32_e32 v230, v230
	v_exp_f32_e32 v231, v231
	v_exp_f32_e32 v232, v232
	v_exp_f32_e32 v233, v233
	v_exp_f32_e32 v234, v234
	v_mfma_f32_32x32x16_bf16 v[82:97], v[166:169], v[146:149], v[82:97]
	ds_read_b128 v[166:169], v201 offset:36864
	v_exp_f32_e32 v235, v235
	v_mov_b32_e32 v17, v220
	v_mov_b32_e32 v219, v221
	v_add_f32_e32 v17, v222, v17
	v_add_f32_e32 v219, v223, v219
	v_add_f32_e32 v17, v224, v17
	v_add_f32_e32 v219, v225, v219
	v_mfma_f32_32x32x16_bf16 v[50:65], v[170:173], v[146:149], v[50:65]
	ds_read_b128 v[170:173], v201 offset:40960
	v_add_f32_e32 v17, v226, v17
	v_add_f32_e32 v219, v227, v219
	v_cvt_pk_bf16_f32 v150, v228, v229
	v_cvt_pk_bf16_f32 v151, v230, v231
	v_cvt_pk_bf16_f32 v152, v232, v233
	v_cvt_pk_bf16_f32 v153, v234, v235
	v_fma_f32 v236, v236, s97, -v2
	v_mfma_f32_32x32x16_bf16 v[18:33], v[174:177], v[146:149], v[18:33]
	ds_read_b128 v[174:177], v201 offset:45056
	v_fma_f32 v237, v237, s97, -v2
	v_fma_f32 v238, v238, s97, -v2
	v_fma_f32 v239, v239, s97, -v2
	v_fma_f32 v240, v240, s97, -v2
	v_fma_f32 v241, v241, s97, -v2
	v_fma_f32 v242, v242, s97, -v2
	v_fma_f32 v243, v243, s97, -v2
	s_waitcnt lgkmcnt(3)
	v_mfma_f32_32x32x16_bf16 v[130:145], v[162:165], v[12:15], v[130:145]
	v_mfma_f32_32x32x16_bf16 v[114:129], v[162:165], v[150:153], v[114:129]
	ds_read_b128 v[162:165], v202 offset:32768
	v_exp_f32_e32 v236, v236
	v_exp_f32_e32 v237, v237
	v_exp_f32_e32 v238, v238
	v_exp_f32_e32 v239, v239
	v_exp_f32_e32 v240, v240
	v_exp_f32_e32 v241, v241
	v_exp_f32_e32 v242, v242
	s_waitcnt lgkmcnt(3)
	v_mfma_f32_32x32x16_bf16 v[98:113], v[166:169], v[12:15], v[98:113]
	v_mfma_f32_32x32x16_bf16 v[82:97], v[166:169], v[150:153], v[82:97]
	ds_read_b128 v[166:169], v202 offset:36864
	v_exp_f32_e32 v243, v243
	v_add_f32_e32 v17, v228, v17
	v_add_f32_e32 v219, v229, v219
	v_add_f32_e32 v17, v230, v17
	v_add_f32_e32 v219, v231, v219
	v_add_f32_e32 v17, v232, v17
	v_add_f32_e32 v219, v233, v219
	s_waitcnt lgkmcnt(3)
	v_mfma_f32_32x32x16_bf16 v[66:81], v[170:173], v[12:15], v[66:81]
	v_mfma_f32_32x32x16_bf16 v[50:65], v[170:173], v[150:153], v[50:65]
	ds_read_b128 v[170:173], v202 offset:40960
	v_add_f32_e32 v17, v234, v17
	v_add_f32_e32 v219, v235, v219
	v_cvt_pk_bf16_f32 v154, v236, v237
	v_cvt_pk_bf16_f32 v155, v238, v239
	v_cvt_pk_bf16_f32 v156, v240, v241
	v_cvt_pk_bf16_f32 v157, v242, v243
	v_fma_f32 v244, v244, s97, -v2
	s_waitcnt lgkmcnt(3)
; DI void attn_item(const Params& p, char* smem, u16* qbase, const u16* gabase, const u16* kbase, const u16* vtbase,
;                   int tkv, int nkt, int mylimit, const float* lam_p, const int g_wave) {
;     ...
; #pragma unroll
;       for (int d = 0; d < 4; ++d) {
;         const int vrow = 32 * d + r;
; #pragma unroll
;         for (int sp = 0; sp < 4; ++sp) {
;           const u32x2 lo = *(const u32x2*)(Vt + vrow * 128 + ((32 * sp) ^ vz) + 8 * hh);
;           const u32x2 hi = *(const u32x2*)(Vt + vrow * 128 + ((32 * sp + 16) ^ vz) + 8 * hh);
;           u32x4 w = {lo[0], lo[1], hi[0], hi[1]};
;           const bf16x8 vf = *reinterpret_cast<bf16x8*>(&w);
;           O0[d] = __builtin_amdgcn_mfma_f32_32x32x16_bf16(vf, pf0[sp], O0[d], 0, 0, 0);
;           O1[d] = __builtin_amdgcn_mfma_f32_32x32x16_bf16(vf, pf1[sp], O1[d], 0, 0, 0);
;         }
;         __builtin_amdgcn_sched_barrier(0);
;       }
;     }
;     asm volatile("s_waitcnt vmcnt(0)" ::: "memory");
;     __syncthreads();
;   }
;     ...
;     u16* qrow = qbase + (size_t)(wid * 32 + r) * 1024;
;     { auto rr = __builtin_amdgcn_permlane32_swap(__float_as_uint(l0), __float_as_uint(l0), false, false);
;       l0 = __uint_as_float(rr[0]) + __uint_as_float(rr[1]); }
;     { auto rr = __builtin_amdgcn_permlane32_swap(__float_as_uint(l1), __float_as_uint(l1), false, false);
;       l1 = __uint_as_float(rr[0]) + __uint_as_float(rr[1]); }
;     const float i0 = 1.f / l0, i1 = *lam_p / l1;
;     float ss = 0.f;
; #pragma unroll
;     for (int d = 0; d < 4; ++d)
; #pragma unroll
;       for (int i = 0; i < 16; ++i) { float v = O0[d][i] * i0 - O1[d][i] * i1; O0[d][i] = v; ss += v * v; }
;     { auto rr = __builtin_amdgcn_permlane32_swap(__float_as_uint(ss), __float_as_uint(ss), false, false);
;       ss = __uint_as_float(rr[0]) + __uint_as_float(rr[1]); }
;     const float rs = rsqrtf(ss * (1.f / 128.f) + 1e-5f) * 0.8f;
;     const u16* garow = gabase + (size_t)(wid * 32 + r) * 1024;
; #pragma unroll
;     for (int d = 0; d < 4; ++d)
; #pragma unroll
;       for (int g = 0; g < 4; ++g) {
;         int dv = 32 * d + 8 * g + 4 * hh;
;         u32x2 gg = *(const u32x2*)(garow + dv);
	v_mfma_f32_32x32x16_bf16 v[34:49], v[174:177], v[12:15], v[34:49]
	v_mfma_f32_32x32x16_bf16 v[18:33], v[174:177], v[150:153], v[18:33]
	ds_read_b128 v[174:177], v202 offset:45056
	v_fma_f32 v245, v245, s97, -v2
	v_fma_f32 v246, v246, s97, -v2
	v_fma_f32 v247, v247, s97, -v2
	v_fma_f32 v248, v248, s97, -v2
	v_fma_f32 v249, v249, s97, -v2
	v_fma_f32 v250, v250, s97, -v2
	v_fma_f32 v251, v251, s97, -v2
	s_waitcnt lgkmcnt(3)
	v_mfma_f32_32x32x16_bf16 v[130:145], v[162:165], v[8:11], v[130:145]
	v_mfma_f32_32x32x16_bf16 v[114:129], v[162:165], v[154:157], v[114:129]
	ds_read_b128 v[162:165], v203 offset:32768
	v_exp_f32_e32 v244, v244
	v_exp_f32_e32 v245, v245
	v_exp_f32_e32 v246, v246
	v_exp_f32_e32 v247, v247
	v_exp_f32_e32 v248, v248
	v_exp_f32_e32 v249, v249
	v_exp_f32_e32 v250, v250
	s_waitcnt lgkmcnt(3)
	v_mfma_f32_32x32x16_bf16 v[98:113], v[166:169], v[8:11], v[98:113]
	v_mfma_f32_32x32x16_bf16 v[82:97], v[166:169], v[154:157], v[82:97]
	ds_read_b128 v[166:169], v203 offset:36864
	v_exp_f32_e32 v251, v251
	v_add_f32_e32 v17, v236, v17
	v_add_f32_e32 v219, v237, v219
	v_add_f32_e32 v17, v238, v17
	v_add_f32_e32 v219, v239, v219
	v_add_f32_e32 v17, v240, v17
	v_add_f32_e32 v219, v241, v219
	s_waitcnt lgkmcnt(3)
	v_mfma_f32_32x32x16_bf16 v[66:81], v[170:173], v[8:11], v[66:81]
	v_mfma_f32_32x32x16_bf16 v[50:65], v[170:173], v[154:157], v[50:65]
	ds_read_b128 v[170:173], v203 offset:40960
	v_add_f32_e32 v17, v242, v17
	v_add_f32_e32 v219, v243, v219
	v_cvt_pk_bf16_f32 v158, v244, v245
	v_cvt_pk_bf16_f32 v159, v246, v247
	v_cvt_pk_bf16_f32 v160, v248, v249
	v_cvt_pk_bf16_f32 v161, v250, v251
	v_add_f32_e32 v17, v244, v17
	s_waitcnt lgkmcnt(3)
	v_mfma_f32_32x32x16_bf16 v[34:49], v[174:177], v[8:11], v[34:49]
	v_mfma_f32_32x32x16_bf16 v[18:33], v[174:177], v[154:157], v[18:33]
	ds_read_b128 v[174:177], v203 offset:45056
	v_add_f32_e32 v219, v245, v219
	v_add_f32_e32 v17, v246, v17
	v_add_f32_e32 v219, v247, v219
	v_add_f32_e32 v17, v248, v17
	v_add_f32_e32 v219, v249, v219
	v_add_f32_e32 v17, v250, v17
	v_add_f32_e32 v219, v251, v219
	s_waitcnt lgkmcnt(3)
	v_mfma_f32_32x32x16_bf16 v[130:145], v[162:165], v[4:7], v[130:145]
	v_mfma_f32_32x32x16_bf16 v[114:129], v[162:165], v[158:161], v[114:129]
	v_add_f32_e32 v17, v17, v219
	s_waitcnt lgkmcnt(2)
	v_mfma_f32_32x32x16_bf16 v[98:113], v[166:169], v[4:7], v[98:113]
	v_mfma_f32_32x32x16_bf16 v[82:97], v[166:169], v[158:161], v[82:97]
	v_add_f32_e32 v187, v187, v17
	s_waitcnt lgkmcnt(1)
	v_mfma_f32_32x32x16_bf16 v[66:81], v[170:173], v[4:7], v[66:81]
	v_mfma_f32_32x32x16_bf16 v[50:65], v[170:173], v[158:161], v[50:65]
	s_waitcnt lgkmcnt(0)
	v_mfma_f32_32x32x16_bf16 v[34:49], v[174:177], v[4:7], v[34:49]
	v_mfma_f32_32x32x16_bf16 v[18:33], v[174:177], v[158:161], v[18:33]
.LBB0_717:
	s_waitcnt vmcnt(0)
	s_addk_i32 s50, 0x4000
	v_lshl_add_u64 v[188:189], v[188:189], 0, s[24:25]
	v_lshl_add_u64 v[190:191], v[190:191], 0, s[24:25]
	v_lshl_add_u64 v[192:193], v[192:193], 0, s[26:27]
	s_cmp_eq_u32 s34, s54
	v_lshl_add_u64 v[194:195], v[194:195], 0, s[26:27]
	s_waitcnt vmcnt(0) lgkmcnt(0)
	s_barrier
	s_cbranch_scc0 .LBB0_709
	s_and_b64 vcc, exec, s[4:5]
	s_cbranch_vccz .LBB0_720
	s_lshl_b64 s[54:55], s[42:43], 1
	s_add_u32 s54, s70, s54
	s_addc_u32 s55, s71, s55
	s_add_u32 s54, s54, s51
	s_addc_u32 s55, s55, 0
	v_ashrrev_i32_e32 v252, 1, v196
	s_movk_i32 s32, 0xffe0
	v_bfi_b32 v252, s32, v252, v196
	v_mov_b32_e32 v253, 0
	v_lshlrev_b64 v[252:253], 11, v[252:253]
	v_lshl_add_u64 v[252:253], s[54:55], 0, v[252:253]
	v_lshrrev_b32_e32 v254, 3, v196
	v_and_b32_e32 v254, 4, v254
	v_lshlrev_b32_e32 v254, 1, v254
	v_mov_b32_e32 v216, v254
	v_mov_b32_e32 v217, 0
	v_lshl_add_u64 v[252:253], v[252:253], 0, v[216:217]
	global_load_dwordx2 v[220:221], v[252:253], off
	global_load_dwordx2 v[222:223], v[252:253], off offset:16
	global_load_dwordx2 v[224:225], v[252:253], off offset:32
	global_load_dwordx2 v[226:227], v[252:253], off offset:48
	global_load_dwordx2 v[228:229], v[252:253], off offset:64
	global_load_dwordx2 v[230:231], v[252:253], off offset:80
	global_load_dwordx2 v[232:233], v[252:253], off offset:96
	global_load_dwordx2 v[234:235], v[252:253], off offset:112
	global_load_dwordx2 v[236:237], v[252:253], off offset:128
	global_load_dwordx2 v[238:239], v[252:253], off offset:144
	global_load_dwordx2 v[240:241], v[252:253], off offset:160
	global_load_dwordx2 v[242:243], v[252:253], off offset:176
	global_load_dwordx2 v[244:245], v[252:253], off offset:192
	global_load_dwordx2 v[246:247], v[252:253], off offset:208
	global_load_dwordx2 v[248:249], v[252:253], off offset:224
	global_load_dwordx2 v[250:251], v[252:253], off offset:240
	v_mov_b32_e32 v2, v196
	ds_read_b32 v8, v3
	v_mov_b32_e32 v6, v186
	v_mov_b32_e32 v7, v187
	s_nop 0
	v_permlane32_swap_b32_e32 v186, v6
	v_permlane32_swap_b32_e32 v187, v7
	v_ashrrev_i32_e32 v4, 1, v2
	s_movk_i32 s34, 0xffe0
	v_pk_add_f32 v[6:7], v[186:187], v[6:7]
	v_bfi_b32 v4, s34, v4, v2
	s_waitcnt lgkmcnt(0)
; DI void attn_item(const Params& p, char* smem, u16* qbase, const u16* gabase, const u16* kbase, const u16* vtbase,
;                   int tkv, int nkt, int mylimit, const float* lam_p, const int g_wave) {
;     ...
;     { auto rr = __builtin_amdgcn_permlane32_swap(__float_as_uint(l0), __float_as_uint(l0), false, false);
;       l0 = __uint_as_float(rr[0]) + __uint_as_float(rr[1]); }
;     { auto rr = __builtin_amdgcn_permlane32_swap(__float_as_uint(l1), __float_as_uint(l1), false, false);
;       l1 = __uint_as_float(rr[0]) + __uint_as_float(rr[1]); }
;     const float i0 = 1.f / l0, i1 = *lam_p / l1;
;     float ss = 0.f;
; #pragma unroll
;     for (int d = 0; d < 4; ++d)
; #pragma unroll
;       for (int i = 0; i < 16; ++i) { float v = O0[d][i] * i0 - O1[d][i] * i1; O0[d][i] = v; ss += v * v; }
	v_div_scale_f32 v9, s[34:35], v7, v7, v8
	v_rcp_f32_e32 v10, v9
	s_lshl_b64 s[4:5], s[42:43], 1
	s_add_u32 s4, s70, s4
	s_addc_u32 s5, s71, s5
	v_fma_f32 v11, -v9, v10, 1.0
	v_fmac_f32_e32 v10, v11, v10
	v_div_scale_f32 v11, vcc, v8, v7, v8
	v_mul_f32_e32 v12, v11, v10
	v_fma_f32 v13, -v9, v12, v11
	v_fmac_f32_e32 v12, v13, v10
	v_fma_f32 v9, -v9, v12, v11
	v_div_fmas_f32 v9, v9, v10, v12
	v_div_fixup_f32 v7, v9, v7, v8
	v_div_scale_f32 v8, s[34:35], v6, v6, 1.0
	v_rcp_f32_e32 v9, v8
	s_add_u32 s4, s4, s51
	v_ashrrev_i32_e32 v5, 31, v4
	v_lshrrev_b32_e32 v2, 3, v2
	v_fma_f32 v10, -v8, v9, 1.0
	v_fmac_f32_e32 v9, v10, v9
	v_div_scale_f32 v10, vcc, 1.0, v6, 1.0
	v_mul_f32_e32 v11, v10, v9
	v_fma_f32 v12, -v8, v11, v10
	v_fmac_f32_e32 v11, v12, v9
	v_fma_f32 v8, -v8, v11, v10
	v_div_fmas_f32 v8, v8, v9, v11
	v_div_fixup_f32 v6, v8, v6, 1.0
	v_mov_b32_e32 v8, v130
	v_mov_b32_e32 v9, v114
	v_mul_f32_e32 v10, v114, v7
	v_pk_fma_f32 v[170:171], v[8:9], v[6:7], v[10:11] op_sel_hi:[1,1,0] neg_lo:[0,0,1] neg_hi:[0,0,1]
	v_mov_b32_e32 v10, v132
	v_mov_b32_e32 v11, v116
	v_mul_f32_e32 v12, v116, v7
	v_mov_b32_e32 v114, v131
	v_mul_f32_e32 v8, v115, v7
	v_pk_fma_f32 v[166:167], v[10:11], v[6:7], v[12:13] op_sel_hi:[1,1,0] neg_lo:[0,0,1] neg_hi:[0,0,1]
	v_mov_b32_e32 v116, v133
	v_mul_f32_e32 v10, v117, v7
	v_pk_fma_f32 v[168:169], v[114:115], v[6:7], v[8:9] op_sel_hi:[1,1,0] neg_lo:[0,0,1] neg_hi:[0,0,1]
	v_pk_fma_f32 v[164:165], v[116:117], v[6:7], v[10:11] op_sel_hi:[1,1,0] neg_lo:[0,0,1] neg_hi:[0,0,1]
	v_mov_b32_e32 v10, v134
	v_mov_b32_e32 v11, v118
	v_mul_f32_e32 v12, v118, v7
	v_pk_mul_f32 v[8:9], v[168:169], v[168:169]
	v_pk_fma_f32 v[162:163], v[10:11], v[6:7], v[12:13] op_sel_hi:[1,1,0] neg_lo:[0,0,1] neg_hi:[0,0,1]
	v_mov_b32_e32 v118, v135
	v_mul_f32_e32 v10, v119, v7
	v_pk_fma_f32 v[8:9], v[170:171], v[170:171], v[8:9]
	v_pk_fma_f32 v[160:161], v[118:119], v[6:7], v[10:11] op_sel_hi:[1,1,0] neg_lo:[0,0,1] neg_hi:[0,0,1]
	v_mov_b32_e32 v10, v136
	v_mov_b32_e32 v11, v120
	v_mul_f32_e32 v12, v120, v7
	v_pk_fma_f32 v[8:9], v[166:167], v[166:167], v[8:9]
	v_pk_fma_f32 v[158:159], v[10:11], v[6:7], v[12:13] op_sel_hi:[1,1,0] neg_lo:[0,0,1] neg_hi:[0,0,1]
	v_mov_b32_e32 v120, v137
	v_mul_f32_e32 v10, v121, v7
	v_pk_fma_f32 v[8:9], v[164:165], v[164:165], v[8:9]
	v_pk_fma_f32 v[156:157], v[120:121], v[6:7], v[10:11] op_sel_hi:[1,1,0] neg_lo:[0,0,1] neg_hi:[0,0,1]
	v_mov_b32_e32 v10, v138
	v_mov_b32_e32 v11, v122
	v_mul_f32_e32 v12, v122, v7
	v_pk_fma_f32 v[8:9], v[162:163], v[162:163], v[8:9]
	v_pk_fma_f32 v[154:155], v[10:11], v[6:7], v[12:13] op_sel_hi:[1,1,0] neg_lo:[0,0,1] neg_hi:[0,0,1]
	v_mov_b32_e32 v122, v139
	v_mul_f32_e32 v10, v123, v7
	v_pk_fma_f32 v[8:9], v[160:161], v[160:161], v[8:9]
	v_pk_fma_f32 v[152:153], v[122:123], v[6:7], v[10:11] op_sel_hi:[1,1,0] neg_lo:[0,0,1] neg_hi:[0,0,1]
	v_mov_b32_e32 v10, v140
	v_mov_b32_e32 v11, v124
	v_mul_f32_e32 v12, v124, v7
	v_pk_fma_f32 v[8:9], v[158:159], v[158:159], v[8:9]
	v_pk_fma_f32 v[150:151], v[10:11], v[6:7], v[12:13] op_sel_hi:[1,1,0] neg_lo:[0,0,1] neg_hi:[0,0,1]
	v_mov_b32_e32 v124, v141
	v_mul_f32_e32 v10, v125, v7
	v_pk_fma_f32 v[8:9], v[156:157], v[156:157], v[8:9]
	v_pk_fma_f32 v[148:149], v[124:125], v[6:7], v[10:11] op_sel_hi:[1,1,0] neg_lo:[0,0,1] neg_hi:[0,0,1]
	v_mov_b32_e32 v10, v142
	v_mov_b32_e32 v11, v126
	v_mul_f32_e32 v12, v126, v7
	v_pk_fma_f32 v[8:9], v[154:155], v[154:155], v[8:9]
	v_pk_fma_f32 v[146:147], v[10:11], v[6:7], v[12:13] op_sel_hi:[1,1,0] neg_lo:[0,0,1] neg_hi:[0,0,1]
	v_mov_b32_e32 v126, v143
	v_mul_f32_e32 v10, v127, v7
	v_pk_fma_f32 v[8:9], v[152:153], v[152:153], v[8:9]
	v_pk_fma_f32 v[140:141], v[126:127], v[6:7], v[10:11] op_sel_hi:[1,1,0] neg_lo:[0,0,1] neg_hi:[0,0,1]
	v_mov_b32_e32 v10, v144
	v_mov_b32_e32 v11, v128
	v_mul_f32_e32 v12, v128, v7
	v_pk_fma_f32 v[8:9], v[150:151], v[150:151], v[8:9]
	v_pk_fma_f32 v[138:139], v[10:11], v[6:7], v[12:13] op_sel_hi:[1,1,0] neg_lo:[0,0,1] neg_hi:[0,0,1]
	v_mov_b32_e32 v128, v145
	v_mul_f32_e32 v10, v129, v7
	v_pk_fma_f32 v[8:9], v[148:149], v[148:149], v[8:9]
	v_pk_fma_f32 v[136:137], v[128:129], v[6:7], v[10:11] op_sel_hi:[1,1,0] neg_lo:[0,0,1] neg_hi:[0,0,1]
	v_mov_b32_e32 v10, v98
	v_mov_b32_e32 v11, v82
	v_mul_f32_e32 v12, v82, v7
	v_pk_fma_f32 v[8:9], v[146:147], v[146:147], v[8:9]
	v_pk_fma_f32 v[134:135], v[10:11], v[6:7], v[12:13] op_sel_hi:[1,1,0] neg_lo:[0,0,1] neg_hi:[0,0,1]
	v_mov_b32_e32 v82, v99
	v_mul_f32_e32 v10, v83, v7
	v_pk_fma_f32 v[8:9], v[140:141], v[140:141], v[8:9]
	v_pk_fma_f32 v[132:133], v[82:83], v[6:7], v[10:11] op_sel_hi:[1,1,0] neg_lo:[0,0,1] neg_hi:[0,0,1]
	v_mov_b32_e32 v10, v100
	v_mov_b32_e32 v11, v84
	v_mul_f32_e32 v12, v84, v7
	v_pk_fma_f32 v[8:9], v[138:139], v[138:139], v[8:9]
	v_pk_fma_f32 v[130:131], v[10:11], v[6:7], v[12:13] op_sel_hi:[1,1,0] neg_lo:[0,0,1] neg_hi:[0,0,1]
	v_mov_b32_e32 v84, v101
	v_mul_f32_e32 v10, v85, v7
	v_pk_fma_f32 v[8:9], v[136:137], v[136:137], v[8:9]
	v_pk_fma_f32 v[128:129], v[84:85], v[6:7], v[10:11] op_sel_hi:[1,1,0] neg_lo:[0,0,1] neg_hi:[0,0,1]
	v_mov_b32_e32 v10, v102
	v_mov_b32_e32 v11, v86
	v_mul_f32_e32 v12, v86, v7
	v_pk_fma_f32 v[8:9], v[134:135], v[134:135], v[8:9]
	v_pk_fma_f32 v[126:127], v[10:11], v[6:7], v[12:13] op_sel_hi:[1,1,0] neg_lo:[0,0,1] neg_hi:[0,0,1]
	v_mov_b32_e32 v86, v103
	v_mul_f32_e32 v10, v87, v7
	v_pk_fma_f32 v[8:9], v[132:133], v[132:133], v[8:9]
	v_pk_fma_f32 v[124:125], v[86:87], v[6:7], v[10:11] op_sel_hi:[1,1,0] neg_lo:[0,0,1] neg_hi:[0,0,1]
	v_mov_b32_e32 v10, v104
	v_mov_b32_e32 v11, v88
	v_mul_f32_e32 v12, v88, v7
	v_pk_fma_f32 v[8:9], v[130:131], v[130:131], v[8:9]
; DI void attn_item(const Params& p, char* smem, u16* qbase, const u16* gabase, const u16* kbase, const u16* vtbase,
;                   int tkv, int nkt, int mylimit, const float* lam_p, const int g_wave) {
;     ...
;     const float i0 = 1.f / l0, i1 = *lam_p / l1;
;     float ss = 0.f;
; #pragma unroll
;     for (int d = 0; d < 4; ++d)
; #pragma unroll
;       for (int i = 0; i < 16; ++i) { float v = O0[d][i] * i0 - O1[d][i] * i1; O0[d][i] = v; ss += v * v; }
	v_pk_fma_f32 v[122:123], v[10:11], v[6:7], v[12:13] op_sel_hi:[1,1,0] neg_lo:[0,0,1] neg_hi:[0,0,1]
	v_mov_b32_e32 v88, v105
	v_mul_f32_e32 v10, v89, v7
	v_pk_fma_f32 v[8:9], v[128:129], v[128:129], v[8:9]
	v_pk_fma_f32 v[120:121], v[88:89], v[6:7], v[10:11] op_sel_hi:[1,1,0] neg_lo:[0,0,1] neg_hi:[0,0,1]
	v_mov_b32_e32 v10, v106
	v_mov_b32_e32 v11, v90
	v_mul_f32_e32 v12, v90, v7
	v_pk_fma_f32 v[8:9], v[126:127], v[126:127], v[8:9]
	v_pk_fma_f32 v[118:119], v[10:11], v[6:7], v[12:13] op_sel_hi:[1,1,0] neg_lo:[0,0,1] neg_hi:[0,0,1]
	v_mov_b32_e32 v90, v107
	v_mul_f32_e32 v10, v91, v7
	v_pk_fma_f32 v[8:9], v[124:125], v[124:125], v[8:9]
	v_pk_fma_f32 v[116:117], v[90:91], v[6:7], v[10:11] op_sel_hi:[1,1,0] neg_lo:[0,0,1] neg_hi:[0,0,1]
	v_mov_b32_e32 v10, v108
	v_mov_b32_e32 v11, v92
	v_mul_f32_e32 v12, v92, v7
	v_pk_fma_f32 v[8:9], v[122:123], v[122:123], v[8:9]
	v_pk_fma_f32 v[114:115], v[10:11], v[6:7], v[12:13] op_sel_hi:[1,1,0] neg_lo:[0,0,1] neg_hi:[0,0,1]
	v_mov_b32_e32 v92, v109
	v_mul_f32_e32 v10, v93, v7
	v_pk_fma_f32 v[8:9], v[120:121], v[120:121], v[8:9]
	v_pk_fma_f32 v[108:109], v[92:93], v[6:7], v[10:11] op_sel_hi:[1,1,0] neg_lo:[0,0,1] neg_hi:[0,0,1]
	v_mov_b32_e32 v10, v110
	v_mov_b32_e32 v11, v94
	v_mul_f32_e32 v12, v94, v7
	v_pk_fma_f32 v[8:9], v[118:119], v[118:119], v[8:9]
	v_pk_fma_f32 v[106:107], v[10:11], v[6:7], v[12:13] op_sel_hi:[1,1,0] neg_lo:[0,0,1] neg_hi:[0,0,1]
	v_mov_b32_e32 v94, v111
	v_mul_f32_e32 v10, v95, v7
	v_pk_fma_f32 v[8:9], v[116:117], v[116:117], v[8:9]
	v_pk_fma_f32 v[104:105], v[94:95], v[6:7], v[10:11] op_sel_hi:[1,1,0] neg_lo:[0,0,1] neg_hi:[0,0,1]
	v_mov_b32_e32 v10, v112
	v_mov_b32_e32 v11, v96
	v_mul_f32_e32 v12, v96, v7
	v_pk_fma_f32 v[8:9], v[114:115], v[114:115], v[8:9]
	v_pk_fma_f32 v[102:103], v[10:11], v[6:7], v[12:13] op_sel_hi:[1,1,0] neg_lo:[0,0,1] neg_hi:[0,0,1]
	v_mov_b32_e32 v96, v113
	v_mul_f32_e32 v10, v97, v7
	v_pk_fma_f32 v[8:9], v[108:109], v[108:109], v[8:9]
	v_pk_fma_f32 v[100:101], v[96:97], v[6:7], v[10:11] op_sel_hi:[1,1,0] neg_lo:[0,0,1] neg_hi:[0,0,1]
	v_mov_b32_e32 v10, v66
	v_mov_b32_e32 v11, v50
	v_mul_f32_e32 v12, v50, v7
	v_pk_fma_f32 v[8:9], v[106:107], v[106:107], v[8:9]
	v_pk_fma_f32 v[98:99], v[10:11], v[6:7], v[12:13] op_sel_hi:[1,1,0] neg_lo:[0,0,1] neg_hi:[0,0,1]
	v_mov_b32_e32 v50, v67
	v_mul_f32_e32 v10, v51, v7
	v_pk_fma_f32 v[8:9], v[104:105], v[104:105], v[8:9]
	v_pk_fma_f32 v[96:97], v[50:51], v[6:7], v[10:11] op_sel_hi:[1,1,0] neg_lo:[0,0,1] neg_hi:[0,0,1]
	v_mov_b32_e32 v10, v68
	v_mov_b32_e32 v11, v52
	v_mul_f32_e32 v12, v52, v7
	v_pk_fma_f32 v[8:9], v[102:103], v[102:103], v[8:9]
	v_pk_fma_f32 v[94:95], v[10:11], v[6:7], v[12:13] op_sel_hi:[1,1,0] neg_lo:[0,0,1] neg_hi:[0,0,1]
	v_mov_b32_e32 v52, v69
	v_mul_f32_e32 v10, v53, v7
	v_pk_fma_f32 v[8:9], v[100:101], v[100:101], v[8:9]
	v_pk_fma_f32 v[92:93], v[52:53], v[6:7], v[10:11] op_sel_hi:[1,1,0] neg_lo:[0,0,1] neg_hi:[0,0,1]
	v_mov_b32_e32 v10, v70
	v_mov_b32_e32 v11, v54
	v_mul_f32_e32 v12, v54, v7
	v_pk_fma_f32 v[8:9], v[98:99], v[98:99], v[8:9]
	v_pk_fma_f32 v[90:91], v[10:11], v[6:7], v[12:13] op_sel_hi:[1,1,0] neg_lo:[0,0,1] neg_hi:[0,0,1]
	v_mov_b32_e32 v54, v71
	v_mul_f32_e32 v10, v55, v7
	v_pk_fma_f32 v[8:9], v[96:97], v[96:97], v[8:9]
	v_pk_fma_f32 v[88:89], v[54:55], v[6:7], v[10:11] op_sel_hi:[1,1,0] neg_lo:[0,0,1] neg_hi:[0,0,1]
	v_mov_b32_e32 v10, v72
	v_mov_b32_e32 v11, v56
	v_mul_f32_e32 v12, v56, v7
	v_pk_fma_f32 v[8:9], v[94:95], v[94:95], v[8:9]
	v_pk_fma_f32 v[86:87], v[10:11], v[6:7], v[12:13] op_sel_hi:[1,1,0] neg_lo:[0,0,1] neg_hi:[0,0,1]
	v_mov_b32_e32 v56, v73
	v_mul_f32_e32 v10, v57, v7
	v_pk_fma_f32 v[8:9], v[92:93], v[92:93], v[8:9]
	v_pk_fma_f32 v[84:85], v[56:57], v[6:7], v[10:11] op_sel_hi:[1,1,0] neg_lo:[0,0,1] neg_hi:[0,0,1]
	v_mov_b32_e32 v10, v74
	v_mov_b32_e32 v11, v58
	v_mul_f32_e32 v12, v58, v7
	v_pk_fma_f32 v[8:9], v[90:91], v[90:91], v[8:9]
	v_pk_fma_f32 v[82:83], v[10:11], v[6:7], v[12:13] op_sel_hi:[1,1,0] neg_lo:[0,0,1] neg_hi:[0,0,1]
	v_mov_b32_e32 v58, v75
	v_mul_f32_e32 v10, v59, v7
	v_pk_fma_f32 v[8:9], v[88:89], v[88:89], v[8:9]
	v_pk_fma_f32 v[72:73], v[58:59], v[6:7], v[10:11] op_sel_hi:[1,1,0] neg_lo:[0,0,1] neg_hi:[0,0,1]
	v_mov_b32_e32 v10, v76
	v_mov_b32_e32 v11, v60
	v_mul_f32_e32 v12, v60, v7
	v_pk_fma_f32 v[8:9], v[86:87], v[86:87], v[8:9]
	v_pk_fma_f32 v[70:71], v[10:11], v[6:7], v[12:13] op_sel_hi:[1,1,0] neg_lo:[0,0,1] neg_hi:[0,0,1]
	v_mov_b32_e32 v60, v77
	v_mul_f32_e32 v10, v61, v7
	v_pk_fma_f32 v[8:9], v[84:85], v[84:85], v[8:9]
	v_pk_fma_f32 v[68:69], v[60:61], v[6:7], v[10:11] op_sel_hi:[1,1,0] neg_lo:[0,0,1] neg_hi:[0,0,1]
	v_mov_b32_e32 v10, v78
	v_mov_b32_e32 v11, v62
	v_mul_f32_e32 v12, v62, v7
	v_pk_fma_f32 v[8:9], v[82:83], v[82:83], v[8:9]
	v_pk_fma_f32 v[66:67], v[10:11], v[6:7], v[12:13] op_sel_hi:[1,1,0] neg_lo:[0,0,1] neg_hi:[0,0,1]
	v_mov_b32_e32 v62, v79
	v_mul_f32_e32 v10, v63, v7
	v_pk_fma_f32 v[8:9], v[72:73], v[72:73], v[8:9]
	v_pk_fma_f32 v[62:63], v[62:63], v[6:7], v[10:11] op_sel_hi:[1,1,0] neg_lo:[0,0,1] neg_hi:[0,0,1]
	v_mov_b32_e32 v10, v80
	v_mov_b32_e32 v11, v64
	v_mul_f32_e32 v12, v64, v7
	v_pk_fma_f32 v[8:9], v[70:71], v[70:71], v[8:9]
	v_pk_fma_f32 v[60:61], v[10:11], v[6:7], v[12:13] op_sel_hi:[1,1,0] neg_lo:[0,0,1] neg_hi:[0,0,1]
	v_mov_b32_e32 v64, v81
	v_mul_f32_e32 v10, v65, v7
	v_pk_fma_f32 v[8:9], v[68:69], v[68:69], v[8:9]
	v_pk_fma_f32 v[58:59], v[64:65], v[6:7], v[10:11] op_sel_hi:[1,1,0] neg_lo:[0,0,1] neg_hi:[0,0,1]
	v_mov_b32_e32 v10, v34
	v_mov_b32_e32 v11, v18
	v_mul_f32_e32 v12, v18, v7
	v_pk_fma_f32 v[8:9], v[66:67], v[66:67], v[8:9]
; DI u32 cvtpk(float lo, float hi) { u32 r; asm volatile("v_cvt_pk_bf16_f32 %0, %1, %2" : "=v"(r) : "v"(lo), "v"(hi)); return r; }
; DI float silu(float x) { return x * __builtin_amdgcn_rcpf(1.f + __expf(-x)); }
; DI void attn_item(const Params& p, char* smem, u16* qbase, const u16* gabase, const u16* kbase, const u16* vtbase,
;                   int tkv, int nkt, int mylimit, const float* lam_p, const int g_wave) {
;     ...
;     for (int d = 0; d < 4; ++d)
; #pragma unroll
;       for (int i = 0; i < 16; ++i) { float v = O0[d][i] * i0 - O1[d][i] * i1; O0[d][i] = v; ss += v * v; }
;     { auto rr = __builtin_amdgcn_permlane32_swap(__float_as_uint(ss), __float_as_uint(ss), false, false);
;       ss = __uint_as_float(rr[0]) + __uint_as_float(rr[1]); }
;     const float rs = rsqrtf(ss * (1.f / 128.f) + 1e-5f) * 0.8f;
;     const u16* garow = gabase + (size_t)(wid * 32 + r) * 1024;
; #pragma unroll
;     for (int d = 0; d < 4; ++d)
; #pragma unroll
;       for (int g = 0; g < 4; ++g) {
;         int dv = 32 * d + 8 * g + 4 * hh;
;         u32x2 gg = *(const u32x2*)(garow + dv);
;         float4 sl = *(const float4*)(p.subln + dv);
;         float g0 = __uint_as_float(gg[0] << 16), g1 = __uint_as_float(gg[0] & 0xffff0000u), g2 = __uint_as_float(gg[1] << 16), g3 = __uint_as_float(gg[1] & 0xffff0000u);
;         float o0 = O0[d][4 * g + 0] * rs * sl.x * silu(g0);
;         float o1 = O0[d][4 * g + 1] * rs * sl.y * silu(g1);
;         float o2 = O0[d][4 * g + 2] * rs * sl.z * silu(g2);
;         float o3 = O0[d][4 * g + 3] * rs * sl.w * silu(g3);
;         u32x2 o; o[0] = cvtpk(o0, o1); o[1] = cvtpk(o2, o3);
;         *(u32x2*)(qrow + dv) = o;
;       }
	v_pk_fma_f32 v[56:57], v[10:11], v[6:7], v[12:13] op_sel_hi:[1,1,0] neg_lo:[0,0,1] neg_hi:[0,0,1]
	v_mov_b32_e32 v18, v35
	v_mul_f32_e32 v10, v19, v7
	v_pk_fma_f32 v[8:9], v[62:63], v[62:63], v[8:9]
	v_pk_fma_f32 v[54:55], v[18:19], v[6:7], v[10:11] op_sel_hi:[1,1,0] neg_lo:[0,0,1] neg_hi:[0,0,1]
	v_mov_b32_e32 v10, v36
	v_mov_b32_e32 v11, v20
	v_mul_f32_e32 v12, v20, v7
	v_pk_fma_f32 v[8:9], v[60:61], v[60:61], v[8:9]
	v_pk_fma_f32 v[52:53], v[10:11], v[6:7], v[12:13] op_sel_hi:[1,1,0] neg_lo:[0,0,1] neg_hi:[0,0,1]
	v_mov_b32_e32 v20, v37
	v_mul_f32_e32 v10, v21, v7
	v_pk_fma_f32 v[8:9], v[58:59], v[58:59], v[8:9]
	v_pk_fma_f32 v[50:51], v[20:21], v[6:7], v[10:11] op_sel_hi:[1,1,0] neg_lo:[0,0,1] neg_hi:[0,0,1]
	v_mov_b32_e32 v10, v38
	v_mov_b32_e32 v11, v22
	v_mul_f32_e32 v12, v22, v7
	v_pk_fma_f32 v[8:9], v[56:57], v[56:57], v[8:9]
	v_pk_fma_f32 v[36:37], v[10:11], v[6:7], v[12:13] op_sel_hi:[1,1,0] neg_lo:[0,0,1] neg_hi:[0,0,1]
	v_mov_b32_e32 v22, v39
	v_mul_f32_e32 v10, v23, v7
	v_pk_fma_f32 v[8:9], v[54:55], v[54:55], v[8:9]
	v_pk_fma_f32 v[34:35], v[22:23], v[6:7], v[10:11] op_sel_hi:[1,1,0] neg_lo:[0,0,1] neg_hi:[0,0,1]
	v_mov_b32_e32 v10, v40
	v_mov_b32_e32 v11, v24
	v_mul_f32_e32 v12, v24, v7
	v_pk_fma_f32 v[8:9], v[52:53], v[52:53], v[8:9]
	v_pk_fma_f32 v[22:23], v[10:11], v[6:7], v[12:13] op_sel_hi:[1,1,0] neg_lo:[0,0,1] neg_hi:[0,0,1]
	v_mov_b32_e32 v24, v41
	v_mul_f32_e32 v10, v25, v7
	v_pk_fma_f32 v[8:9], v[50:51], v[50:51], v[8:9]
	v_pk_fma_f32 v[20:21], v[24:25], v[6:7], v[10:11] op_sel_hi:[1,1,0] neg_lo:[0,0,1] neg_hi:[0,0,1]
	v_mov_b32_e32 v10, v42
	v_mov_b32_e32 v11, v26
	v_mul_f32_e32 v12, v26, v7
	v_pk_fma_f32 v[8:9], v[36:37], v[36:37], v[8:9]
	v_pk_fma_f32 v[16:17], v[10:11], v[6:7], v[12:13] op_sel_hi:[1,1,0] neg_lo:[0,0,1] neg_hi:[0,0,1]
	v_mov_b32_e32 v26, v43
	v_mul_f32_e32 v10, v27, v7
	v_pk_fma_f32 v[8:9], v[34:35], v[34:35], v[8:9]
	v_pk_fma_f32 v[14:15], v[26:27], v[6:7], v[10:11] op_sel_hi:[1,1,0] neg_lo:[0,0,1] neg_hi:[0,0,1]
	v_mov_b32_e32 v10, v44
	v_mov_b32_e32 v11, v28
	v_mov_b32_e32 v28, v45
	v_pk_fma_f32 v[8:9], v[22:23], v[22:23], v[8:9]
	v_pk_mul_f32 v[10:11], v[10:11], v[6:7]
	v_pk_mul_f32 v[12:13], v[28:29], v[6:7]
	v_pk_fma_f32 v[8:9], v[20:21], v[20:21], v[8:9]
	v_mov_b32_e32 v18, v12
	v_mov_b32_e32 v19, v10
	v_mov_b32_e32 v10, v13
	v_pk_fma_f32 v[8:9], v[16:17], v[16:17], v[8:9]
	v_pk_add_f32 v[12:13], v[18:19], v[10:11] neg_lo:[0,1] neg_hi:[0,1]
	v_pk_fma_f32 v[8:9], v[14:15], v[14:15], v[8:9]
	v_mul_f32_e32 v10, v13, v13
	v_pk_add_f32 v[8:9], v[10:11], v[8:9] op_sel_hi:[0,1]
	v_mov_b32_e32 v10, v46
	v_mov_b32_e32 v11, v30
	v_mov_b32_e32 v30, v47
	v_pk_mul_f32 v[10:11], v[10:11], v[6:7]
	v_pk_mul_f32 v[18:19], v[30:31], v[6:7]
	v_mov_b32_e32 v25, v10
	v_mov_b32_e32 v24, v18
	v_mov_b32_e32 v10, v19
	v_pk_add_f32 v[10:11], v[24:25], v[10:11] neg_lo:[0,1] neg_hi:[0,1]
	v_pk_fma_f32 v[8:9], v[12:13], v[12:13], v[8:9]
	v_mul_f32_e32 v18, v11, v11
	v_pk_add_f32 v[8:9], v[18:19], v[8:9] op_sel_hi:[0,1]
	v_pk_fma_f32 v[18:19], v[10:11], v[10:11], v[8:9]
	v_mov_b32_e32 v8, v48
	v_mov_b32_e32 v9, v32
	v_mov_b32_e32 v32, v49
	v_pk_mul_f32 v[8:9], v[8:9], v[6:7]
	v_pk_mul_f32 v[6:7], v[32:33], v[6:7]
	v_mov_b32_e32 v25, v8
	v_mov_b32_e32 v24, v6
	v_mov_b32_e32 v8, v7
	v_pk_add_f32 v[8:9], v[24:25], v[8:9] neg_lo:[0,1] neg_hi:[0,1]
	s_addc_u32 s5, s5, 0
	v_mul_f32_e32 v6, v9, v9
	v_pk_add_f32 v[6:7], v[6:7], v[18:19] op_sel_hi:[0,1]
	v_pk_fma_f32 v[6:7], v[8:9], v[8:9], v[6:7]
	v_lshlrev_b64 v[4:5], 11, v[4:5]
	v_mov_b32_e32 v7, v6
	s_nop 1
	v_permlane32_swap_b32_e32 v6, v7
	v_add_f32_e32 v6, v6, v7
	v_mov_b32_e32 v7, 0x3727c5ac
	v_fmamk_f32 v6, v6, 0x3c000000, v7
	v_cmp_gt_f32_e32 vcc, s98, v6
	v_mul_f32_e32 v7, 0x4b800000, v6
	v_lshl_add_u64 v[24:25], s[0:1], 0, v[4:5]
	v_cndmask_b32_e32 v6, v6, v7, vcc
	v_rsq_f32_e32 v6, v6
	v_lshl_add_u64 v[4:5], s[4:5], 0, v[4:5]
	v_mul_f32_e32 v7, 0x45800000, v6
	v_cndmask_b32_e32 v6, v6, v7, vcc
	v_mul_f32_e32 v15, 0x3f4ccccd, v6
	v_and_b32_e32 v6, 4, v2
	v_lshlrev_b32_e32 v2, 1, v6
	v_lshl_add_u64 v[18:19], v[4:5], 0, v[2:3]
	s_waitcnt vmcnt(0)
	v_mov_b32_e32 v26, v220
	v_mov_b32_e32 v27, v221
	v_lshlrev_b32_e32 v17, 2, v6
	v_add_u32_e32 v219, 0x25100, v17
	ds_read_b128 v[4:7], v219
	v_mul_f32_e32 v31, v166, v15
	v_mul_f32_e32 v33, v164, v15
	v_mul_f32_e32 v29, v170, v15
	v_mul_f32_e32 v20, v20, v15
	v_mul_f32_e32 v12, v12, v15
	v_mul_f32_e32 v10, v10, v15
	v_mul_f32_e32 v8, v8, v15
	v_lshlrev_b32_e32 v28, 16, v26
	v_and_b32_e32 v26, 0xffff0000, v26
	s_waitcnt lgkmcnt(0)
	v_mov_b32_e32 v39, v4
	v_mul_f32_e32 v4, 0xbfb8aa3b, v26
	v_exp_f32_e32 v4, v4
	v_lshlrev_b32_e32 v30, 16, v27
	v_and_b32_e32 v32, 0xffff0000, v27
	v_mul_f32_e32 v27, v168, v15
	v_add_f32_e32 v4, 1.0, v4
	v_rcp_f32_e32 v4, v4
	v_mul_f32_e32 v21, 0xbfb8aa3b, v28
	v_exp_f32_e32 v21, v21
	v_pk_mul_f32 v[4:5], v[4:5], v[26:27]
	s_nop 0
	v_mul_f32_e32 v23, v4, v5
	v_mul_f32_e32 v4, 0xbfb8aa3b, v30
	v_exp_f32_e32 v4, v4
	v_mov_b32_e32 v5, v6
	v_add_f32_e32 v21, 1.0, v21
	v_rcp_f32_e32 v38, v21
	v_add_f32_e32 v4, 1.0, v4
	v_rcp_f32_e32 v4, v4
	v_pk_mul_f32 v[28:29], v[38:39], v[28:29]
	s_nop 0
	v_mul_f32_e32 v21, v28, v29
	v_pk_mul_f32 v[4:5], v[4:5], v[30:31]
	v_mul_f32_e32 v28, v162, v15
	v_mul_f32_e32 v26, v4, v5
	v_mul_f32_e32 v4, 0xbfb8aa3b, v32
	v_exp_f32_e32 v4, v4
	v_mul_f32_e32 v30, v160, v15
	v_add_f32_e32 v4, 1.0, v4
	v_rcp_f32_e32 v6, v4
	s_nop 0
	v_pk_mul_f32 v[4:5], v[6:7], v[32:33]
	s_nop 0
	v_mul_f32_e32 v4, v4, v5
	v_cvt_pk_bf16_f32 v6, v21, v23
	v_cvt_pk_bf16_f32 v7, v26, v4
	v_lshl_add_u64 v[4:5], v[24:25], 0, v[2:3]
	global_store_dwordx2 v[4:5], v[6:7], off
	v_mov_b32_e32 v6, v222
	v_mov_b32_e32 v7, v223
	s_nop 0
	ds_read_b128 v[24:27], v219 offset:32
	v_lshlrev_b32_e32 v29, 16, v6
	v_mul_f32_e32 v2, 0xbfb8aa3b, v29
	v_exp_f32_e32 v2, v2
	v_and_b32_e32 v31, 0xffff0000, v6
	v_mul_f32_e32 v6, 0xbfb8aa3b, v31
	v_exp_f32_e32 v6, v6
	v_add_f32_e32 v2, 1.0, v2
	v_rcp_f32_e32 v39, v2
	s_waitcnt lgkmcnt(0)
; DI u32 cvtpk(float lo, float hi) { u32 r; asm volatile("v_cvt_pk_bf16_f32 %0, %1, %2" : "=v"(r) : "v"(lo), "v"(hi)); return r; }
; DI float silu(float x) { return x * __builtin_amdgcn_rcpf(1.f + __expf(-x)); }
; DI void attn_item(const Params& p, char* smem, u16* qbase, const u16* gabase, const u16* kbase, const u16* vtbase,
;                   int tkv, int nkt, int mylimit, const float* lam_p, const int g_wave) {
;     ...
; #pragma unroll
;     for (int d = 0; d < 4; ++d)
; #pragma unroll
;       for (int g = 0; g < 4; ++g) {
;         int dv = 32 * d + 8 * g + 4 * hh;
;         u32x2 gg = *(const u32x2*)(garow + dv);
;         float4 sl = *(const float4*)(p.subln + dv);
;         float g0 = __uint_as_float(gg[0] << 16), g1 = __uint_as_float(gg[0] & 0xffff0000u), g2 = __uint_as_float(gg[1] << 16), g3 = __uint_as_float(gg[1] & 0xffff0000u);
;         float o0 = O0[d][4 * g + 0] * rs * sl.x * silu(g0);
;         float o1 = O0[d][4 * g + 1] * rs * sl.y * silu(g1);
;         float o2 = O0[d][4 * g + 2] * rs * sl.z * silu(g2);
;         float o3 = O0[d][4 * g + 3] * rs * sl.w * silu(g3);
;         u32x2 o; o[0] = cvtpk(o0, o1); o[1] = cvtpk(o2, o3);
;         *(u32x2*)(qrow + dv) = o;
;       }
	v_mov_b32_e32 v38, v24
	v_lshlrev_b32_e32 v33, 16, v7
	v_add_f32_e32 v6, 1.0, v6
	v_pk_mul_f32 v[28:29], v[38:39], v[28:29]
	v_and_b32_e32 v7, 0xffff0000, v7
	v_mul_f32_e32 v2, v28, v29
	v_rcp_f32_e32 v29, v6
	v_mul_f32_e32 v6, 0xbfb8aa3b, v33
	v_exp_f32_e32 v6, v6
	v_mov_b32_e32 v28, v25
	v_pk_mul_f32 v[24:25], v[28:29], v[30:31]
	v_mov_b32_e32 v32, v26
	v_add_f32_e32 v6, 1.0, v6
	v_mul_f32_e32 v21, v24, v25
	v_rcp_f32_e32 v25, v6
	v_mul_f32_e32 v6, 0xbfb8aa3b, v7
	v_exp_f32_e32 v6, v6
	v_mul_f32_e32 v24, v158, v15
	v_pk_mul_f32 v[24:25], v[24:25], v[32:33]
	v_mul_f32_e32 v38, v154, v15
	v_add_f32_e32 v6, 1.0, v6
	v_mul_f32_e32 v23, v24, v25
	v_rcp_f32_e32 v25, v6
	v_mul_f32_e32 v24, v156, v15
	v_mov_b32_e32 v6, v27
	v_pk_mul_f32 v[6:7], v[24:25], v[6:7]
	s_nop 0
	v_mul_f32_e32 v7, v6, v7
	v_cvt_pk_bf16_f32 v6, v2, v21
	v_cvt_pk_bf16_f32 v7, v23, v7
	global_store_dwordx2 v[4:5], v[6:7], off offset:16
	v_mov_b32_e32 v6, v224
	v_mov_b32_e32 v7, v225
	s_nop 0
	ds_read_b128 v[24:27], v219 offset:64
	v_lshlrev_b32_e32 v29, 16, v6
	v_mul_f32_e32 v2, 0xbfb8aa3b, v29
	v_exp_f32_e32 v2, v2
	v_and_b32_e32 v31, 0xffff0000, v6
	v_mul_f32_e32 v6, 0xbfb8aa3b, v31
	v_exp_f32_e32 v6, v6
	v_add_f32_e32 v2, 1.0, v2
	v_rcp_f32_e32 v39, v2
	s_waitcnt lgkmcnt(0)
	v_mov_b32_e32 v28, v24
	v_lshlrev_b32_e32 v33, 16, v7
	v_add_f32_e32 v6, 1.0, v6
	v_pk_mul_f32 v[28:29], v[38:39], v[28:29]
	v_mov_b32_e32 v30, v25
	v_mul_f32_e32 v2, v28, v29
	v_rcp_f32_e32 v29, v6
	v_mul_f32_e32 v6, 0xbfb8aa3b, v33
	v_exp_f32_e32 v6, v6
	v_mul_f32_e32 v28, v152, v15
	v_and_b32_e32 v7, 0xffff0000, v7
	v_pk_mul_f32 v[24:25], v[28:29], v[30:31]
	v_add_f32_e32 v6, 1.0, v6
	v_mul_f32_e32 v21, v24, v25
	v_rcp_f32_e32 v25, v6
	v_mul_f32_e32 v6, 0xbfb8aa3b, v7
	v_exp_f32_e32 v6, v6
	v_mul_f32_e32 v24, v150, v15
	v_mov_b32_e32 v32, v26
	v_pk_mul_f32 v[24:25], v[24:25], v[32:33]
	v_add_f32_e32 v6, 1.0, v6
	v_mul_f32_e32 v23, v24, v25
	v_rcp_f32_e32 v25, v6
	v_mul_f32_e32 v24, v148, v15
	v_mov_b32_e32 v6, v27
	v_mul_f32_e32 v38, v146, v15
	v_pk_mul_f32 v[6:7], v[24:25], v[6:7]
	s_nop 0
	v_mul_f32_e32 v7, v6, v7
	v_cvt_pk_bf16_f32 v6, v2, v21
	v_cvt_pk_bf16_f32 v7, v23, v7
	global_store_dwordx2 v[4:5], v[6:7], off offset:32
	v_mov_b32_e32 v6, v226
	v_mov_b32_e32 v7, v227
	s_nop 0
	ds_read_b128 v[24:27], v219 offset:96
	v_lshlrev_b32_e32 v29, 16, v6
	v_mul_f32_e32 v2, 0xbfb8aa3b, v29
	v_exp_f32_e32 v2, v2
	v_and_b32_e32 v31, 0xffff0000, v6
	v_mul_f32_e32 v6, 0xbfb8aa3b, v31
	v_exp_f32_e32 v6, v6
	v_add_f32_e32 v2, 1.0, v2
	v_rcp_f32_e32 v39, v2
	s_waitcnt lgkmcnt(0)
	v_mov_b32_e32 v28, v24
	v_lshlrev_b32_e32 v33, 16, v7
	v_add_f32_e32 v6, 1.0, v6
	v_pk_mul_f32 v[28:29], v[38:39], v[28:29]
	v_mov_b32_e32 v30, v25
	v_mul_f32_e32 v2, v28, v29
	v_rcp_f32_e32 v29, v6
	v_mul_f32_e32 v6, 0xbfb8aa3b, v33
	v_exp_f32_e32 v6, v6
	v_mul_f32_e32 v28, v140, v15
	v_and_b32_e32 v7, 0xffff0000, v7
	v_pk_mul_f32 v[24:25], v[28:29], v[30:31]
	v_add_f32_e32 v6, 1.0, v6
	v_mul_f32_e32 v21, v24, v25
	v_rcp_f32_e32 v25, v6
	v_mul_f32_e32 v6, 0xbfb8aa3b, v7
	v_exp_f32_e32 v6, v6
	v_mul_f32_e32 v24, v138, v15
	v_mov_b32_e32 v32, v26
	v_pk_mul_f32 v[24:25], v[24:25], v[32:33]
	v_add_f32_e32 v6, 1.0, v6
	v_mul_f32_e32 v23, v24, v25
	v_rcp_f32_e32 v25, v6
	v_mul_f32_e32 v24, v136, v15
	v_mov_b32_e32 v6, v27
	v_mul_f32_e32 v38, v134, v15
	v_pk_mul_f32 v[6:7], v[24:25], v[6:7]
	s_nop 0
	v_mul_f32_e32 v7, v6, v7
	v_cvt_pk_bf16_f32 v6, v2, v21
	v_cvt_pk_bf16_f32 v7, v23, v7
	global_store_dwordx2 v[4:5], v[6:7], off offset:48
	v_mov_b32_e32 v6, v228
	v_mov_b32_e32 v7, v229
	s_nop 0
	ds_read_b128 v[24:27], v219 offset:128
	v_lshlrev_b32_e32 v29, 16, v6
	v_mul_f32_e32 v2, 0xbfb8aa3b, v29
	v_exp_f32_e32 v2, v2
	v_and_b32_e32 v31, 0xffff0000, v6
	v_mul_f32_e32 v6, 0xbfb8aa3b, v31
	v_exp_f32_e32 v6, v6
	v_add_f32_e32 v2, 1.0, v2
	v_rcp_f32_e32 v39, v2
	s_waitcnt lgkmcnt(0)
	v_mov_b32_e32 v28, v24
	v_lshlrev_b32_e32 v33, 16, v7
	v_add_f32_e32 v6, 1.0, v6
	v_pk_mul_f32 v[28:29], v[38:39], v[28:29]
	v_mov_b32_e32 v30, v25
	v_mul_f32_e32 v2, v28, v29
	v_rcp_f32_e32 v29, v6
	v_mul_f32_e32 v6, 0xbfb8aa3b, v33
	v_exp_f32_e32 v6, v6
	v_mul_f32_e32 v28, v132, v15
	v_and_b32_e32 v7, 0xffff0000, v7
	v_pk_mul_f32 v[24:25], v[28:29], v[30:31]
	v_add_f32_e32 v6, 1.0, v6
	v_mul_f32_e32 v21, v24, v25
	v_rcp_f32_e32 v25, v6
	v_mul_f32_e32 v6, 0xbfb8aa3b, v7
	v_exp_f32_e32 v6, v6
	v_mul_f32_e32 v24, v130, v15
	v_mov_b32_e32 v32, v26
	v_pk_mul_f32 v[24:25], v[24:25], v[32:33]
	v_add_f32_e32 v6, 1.0, v6
	v_mul_f32_e32 v23, v24, v25
	v_rcp_f32_e32 v25, v6
	v_mul_f32_e32 v24, v128, v15
	v_mov_b32_e32 v6, v27
	v_mul_f32_e32 v38, v126, v15
	v_pk_mul_f32 v[6:7], v[24:25], v[6:7]
	s_nop 0
	v_mul_f32_e32 v7, v6, v7
	v_cvt_pk_bf16_f32 v6, v2, v21
	v_cvt_pk_bf16_f32 v7, v23, v7
	global_store_dwordx2 v[4:5], v[6:7], off offset:64
	v_mov_b32_e32 v6, v230
	v_mov_b32_e32 v7, v231
	s_nop 0
	ds_read_b128 v[24:27], v219 offset:160
	v_lshlrev_b32_e32 v29, 16, v6
	v_mul_f32_e32 v2, 0xbfb8aa3b, v29
	v_exp_f32_e32 v2, v2
	v_and_b32_e32 v31, 0xffff0000, v6
	v_mul_f32_e32 v6, 0xbfb8aa3b, v31
	v_exp_f32_e32 v6, v6
	v_add_f32_e32 v2, 1.0, v2
	v_rcp_f32_e32 v39, v2
	s_waitcnt lgkmcnt(0)
; DI u32 cvtpk(float lo, float hi) { u32 r; asm volatile("v_cvt_pk_bf16_f32 %0, %1, %2" : "=v"(r) : "v"(lo), "v"(hi)); return r; }
; DI float silu(float x) { return x * __builtin_amdgcn_rcpf(1.f + __expf(-x)); }
; DI void attn_item(const Params& p, char* smem, u16* qbase, const u16* gabase, const u16* kbase, const u16* vtbase,
;                   int tkv, int nkt, int mylimit, const float* lam_p, const int g_wave) {
;     ...
; #pragma unroll
;     for (int d = 0; d < 4; ++d)
; #pragma unroll
;       for (int g = 0; g < 4; ++g) {
;         int dv = 32 * d + 8 * g + 4 * hh;
;         u32x2 gg = *(const u32x2*)(garow + dv);
;         float4 sl = *(const float4*)(p.subln + dv);
;         float g0 = __uint_as_float(gg[0] << 16), g1 = __uint_as_float(gg[0] & 0xffff0000u), g2 = __uint_as_float(gg[1] << 16), g3 = __uint_as_float(gg[1] & 0xffff0000u);
;         float o0 = O0[d][4 * g + 0] * rs * sl.x * silu(g0);
;         float o1 = O0[d][4 * g + 1] * rs * sl.y * silu(g1);
;         float o2 = O0[d][4 * g + 2] * rs * sl.z * silu(g2);
;         float o3 = O0[d][4 * g + 3] * rs * sl.w * silu(g3);
;         u32x2 o; o[0] = cvtpk(o0, o1); o[1] = cvtpk(o2, o3);
;         *(u32x2*)(qrow + dv) = o;
;       }
	v_mov_b32_e32 v28, v24
	v_lshlrev_b32_e32 v33, 16, v7
	v_add_f32_e32 v6, 1.0, v6
	v_pk_mul_f32 v[28:29], v[38:39], v[28:29]
	v_mov_b32_e32 v30, v25
	v_mul_f32_e32 v2, v28, v29
	v_rcp_f32_e32 v29, v6
	v_mul_f32_e32 v6, 0xbfb8aa3b, v33
	v_exp_f32_e32 v6, v6
	v_mul_f32_e32 v28, v124, v15
	v_and_b32_e32 v7, 0xffff0000, v7
	v_pk_mul_f32 v[24:25], v[28:29], v[30:31]
	v_add_f32_e32 v6, 1.0, v6
	v_mul_f32_e32 v21, v24, v25
	v_rcp_f32_e32 v25, v6
	v_mul_f32_e32 v6, 0xbfb8aa3b, v7
	v_exp_f32_e32 v6, v6
	v_mul_f32_e32 v24, v122, v15
	v_mov_b32_e32 v32, v26
	v_pk_mul_f32 v[24:25], v[24:25], v[32:33]
	v_add_f32_e32 v6, 1.0, v6
	v_mul_f32_e32 v23, v24, v25
	v_rcp_f32_e32 v25, v6
	v_mul_f32_e32 v24, v120, v15
	v_mov_b32_e32 v6, v27
	v_mul_f32_e32 v38, v118, v15
	v_pk_mul_f32 v[6:7], v[24:25], v[6:7]
	s_nop 0
	v_mul_f32_e32 v7, v6, v7
	v_cvt_pk_bf16_f32 v6, v2, v21
	v_cvt_pk_bf16_f32 v7, v23, v7
	global_store_dwordx2 v[4:5], v[6:7], off offset:80
	v_mov_b32_e32 v6, v232
	v_mov_b32_e32 v7, v233
	s_nop 0
	ds_read_b128 v[24:27], v219 offset:192
	v_lshlrev_b32_e32 v29, 16, v6
	v_mul_f32_e32 v2, 0xbfb8aa3b, v29
	v_exp_f32_e32 v2, v2
	v_and_b32_e32 v31, 0xffff0000, v6
	v_mul_f32_e32 v6, 0xbfb8aa3b, v31
	v_exp_f32_e32 v6, v6
	v_add_f32_e32 v2, 1.0, v2
	v_rcp_f32_e32 v39, v2
	s_waitcnt lgkmcnt(0)
	v_mov_b32_e32 v28, v24
	v_lshlrev_b32_e32 v33, 16, v7
	v_add_f32_e32 v6, 1.0, v6
	v_pk_mul_f32 v[28:29], v[38:39], v[28:29]
	v_mov_b32_e32 v30, v25
	v_mul_f32_e32 v2, v28, v29
	v_rcp_f32_e32 v29, v6
	v_mul_f32_e32 v6, 0xbfb8aa3b, v33
	v_exp_f32_e32 v6, v6
	v_mul_f32_e32 v28, v116, v15
	v_and_b32_e32 v7, 0xffff0000, v7
	v_pk_mul_f32 v[24:25], v[28:29], v[30:31]
	v_add_f32_e32 v6, 1.0, v6
	v_mul_f32_e32 v21, v24, v25
	v_rcp_f32_e32 v25, v6
	v_mul_f32_e32 v6, 0xbfb8aa3b, v7
	v_exp_f32_e32 v6, v6
	v_mul_f32_e32 v24, v114, v15
	v_mov_b32_e32 v32, v26
	v_pk_mul_f32 v[24:25], v[24:25], v[32:33]
	v_add_f32_e32 v6, 1.0, v6
	v_mul_f32_e32 v23, v24, v25
	v_rcp_f32_e32 v25, v6
	v_mul_f32_e32 v24, v108, v15
	v_mov_b32_e32 v6, v27
	v_mul_f32_e32 v38, v106, v15
	v_pk_mul_f32 v[6:7], v[24:25], v[6:7]
	s_nop 0
	v_mul_f32_e32 v7, v6, v7
	v_cvt_pk_bf16_f32 v6, v2, v21
	v_cvt_pk_bf16_f32 v7, v23, v7
	global_store_dwordx2 v[4:5], v[6:7], off offset:96
	v_mov_b32_e32 v6, v234
	v_mov_b32_e32 v7, v235
	s_nop 0
	ds_read_b128 v[24:27], v219 offset:224
	v_lshlrev_b32_e32 v29, 16, v6
	v_mul_f32_e32 v2, 0xbfb8aa3b, v29
	v_exp_f32_e32 v2, v2
	v_and_b32_e32 v31, 0xffff0000, v6
	v_mul_f32_e32 v6, 0xbfb8aa3b, v31
	v_exp_f32_e32 v6, v6
	v_add_f32_e32 v2, 1.0, v2
	v_rcp_f32_e32 v39, v2
	s_waitcnt lgkmcnt(0)
	v_mov_b32_e32 v28, v24
	v_lshlrev_b32_e32 v33, 16, v7
	v_add_f32_e32 v6, 1.0, v6
	v_pk_mul_f32 v[28:29], v[38:39], v[28:29]
	v_mov_b32_e32 v30, v25
	v_mul_f32_e32 v2, v28, v29
	v_rcp_f32_e32 v29, v6
	v_mul_f32_e32 v6, 0xbfb8aa3b, v33
	v_exp_f32_e32 v6, v6
	v_mul_f32_e32 v28, v104, v15
	v_and_b32_e32 v7, 0xffff0000, v7
	v_pk_mul_f32 v[24:25], v[28:29], v[30:31]
	v_add_f32_e32 v6, 1.0, v6
	v_mul_f32_e32 v21, v24, v25
	v_rcp_f32_e32 v25, v6
	v_mul_f32_e32 v6, 0xbfb8aa3b, v7
	v_exp_f32_e32 v6, v6
	v_mul_f32_e32 v24, v102, v15
	v_mov_b32_e32 v32, v26
	v_pk_mul_f32 v[24:25], v[24:25], v[32:33]
	v_add_f32_e32 v6, 1.0, v6
	v_mul_f32_e32 v23, v24, v25
	v_rcp_f32_e32 v25, v6
	v_mul_f32_e32 v24, v100, v15
	v_mov_b32_e32 v6, v27
	v_mul_f32_e32 v38, v98, v15
	v_pk_mul_f32 v[6:7], v[24:25], v[6:7]
	s_nop 0
	v_mul_f32_e32 v7, v6, v7
	v_cvt_pk_bf16_f32 v6, v2, v21
	v_cvt_pk_bf16_f32 v7, v23, v7
	global_store_dwordx2 v[4:5], v[6:7], off offset:112
	v_mov_b32_e32 v6, v236
	v_mov_b32_e32 v7, v237
	s_nop 0
	ds_read_b128 v[24:27], v219 offset:256
	v_lshlrev_b32_e32 v29, 16, v6
	v_mul_f32_e32 v2, 0xbfb8aa3b, v29
	v_exp_f32_e32 v2, v2
	v_and_b32_e32 v31, 0xffff0000, v6
	v_mul_f32_e32 v6, 0xbfb8aa3b, v31
	v_exp_f32_e32 v6, v6
	v_add_f32_e32 v2, 1.0, v2
	v_rcp_f32_e32 v39, v2
	s_waitcnt lgkmcnt(0)
	v_mov_b32_e32 v28, v24
	v_lshlrev_b32_e32 v33, 16, v7
	v_add_f32_e32 v6, 1.0, v6
	v_pk_mul_f32 v[28:29], v[38:39], v[28:29]
	v_mov_b32_e32 v30, v25
	v_mul_f32_e32 v2, v28, v29
	v_rcp_f32_e32 v29, v6
	v_mul_f32_e32 v6, 0xbfb8aa3b, v33
	v_exp_f32_e32 v6, v6
	v_mul_f32_e32 v28, v96, v15
	v_and_b32_e32 v7, 0xffff0000, v7
	v_pk_mul_f32 v[24:25], v[28:29], v[30:31]
	v_add_f32_e32 v6, 1.0, v6
	v_mul_f32_e32 v21, v24, v25
	v_rcp_f32_e32 v25, v6
	v_mul_f32_e32 v6, 0xbfb8aa3b, v7
	v_exp_f32_e32 v6, v6
	v_mul_f32_e32 v24, v94, v15
	v_mov_b32_e32 v32, v26
	v_pk_mul_f32 v[24:25], v[24:25], v[32:33]
	v_add_f32_e32 v6, 1.0, v6
	v_mul_f32_e32 v23, v24, v25
	v_rcp_f32_e32 v25, v6
	v_mul_f32_e32 v24, v92, v15
	v_mov_b32_e32 v6, v27
	v_mul_f32_e32 v38, v90, v15
	v_pk_mul_f32 v[6:7], v[24:25], v[6:7]
	s_nop 0
	v_mul_f32_e32 v7, v6, v7
	v_cvt_pk_bf16_f32 v6, v2, v21
	v_cvt_pk_bf16_f32 v7, v23, v7
	global_store_dwordx2 v[4:5], v[6:7], off offset:128
	v_mov_b32_e32 v6, v238
	v_mov_b32_e32 v7, v239
	s_nop 0
	ds_read_b128 v[24:27], v219 offset:288
	v_lshlrev_b32_e32 v29, 16, v6
	v_mul_f32_e32 v2, 0xbfb8aa3b, v29
	v_exp_f32_e32 v2, v2
	v_and_b32_e32 v31, 0xffff0000, v6
	v_mul_f32_e32 v6, 0xbfb8aa3b, v31
	v_exp_f32_e32 v6, v6
	v_add_f32_e32 v2, 1.0, v2
	v_rcp_f32_e32 v39, v2
	s_waitcnt lgkmcnt(0)
; DI u32 cvtpk(float lo, float hi) { u32 r; asm volatile("v_cvt_pk_bf16_f32 %0, %1, %2" : "=v"(r) : "v"(lo), "v"(hi)); return r; }
; DI float silu(float x) { return x * __builtin_amdgcn_rcpf(1.f + __expf(-x)); }
; DI void attn_item(const Params& p, char* smem, u16* qbase, const u16* gabase, const u16* kbase, const u16* vtbase,
;                   int tkv, int nkt, int mylimit, const float* lam_p, const int g_wave) {
;     ...
; #pragma unroll
;     for (int d = 0; d < 4; ++d)
; #pragma unroll
;       for (int g = 0; g < 4; ++g) {
;         int dv = 32 * d + 8 * g + 4 * hh;
;         u32x2 gg = *(const u32x2*)(garow + dv);
;         float4 sl = *(const float4*)(p.subln + dv);
;         float g0 = __uint_as_float(gg[0] << 16), g1 = __uint_as_float(gg[0] & 0xffff0000u), g2 = __uint_as_float(gg[1] << 16), g3 = __uint_as_float(gg[1] & 0xffff0000u);
;         float o0 = O0[d][4 * g + 0] * rs * sl.x * silu(g0);
;         float o1 = O0[d][4 * g + 1] * rs * sl.y * silu(g1);
;         float o2 = O0[d][4 * g + 2] * rs * sl.z * silu(g2);
;         float o3 = O0[d][4 * g + 3] * rs * sl.w * silu(g3);
;         u32x2 o; o[0] = cvtpk(o0, o1); o[1] = cvtpk(o2, o3);
;         *(u32x2*)(qrow + dv) = o;
;       }
	v_mov_b32_e32 v28, v24
	v_lshlrev_b32_e32 v33, 16, v7
	v_add_f32_e32 v6, 1.0, v6
	v_pk_mul_f32 v[28:29], v[38:39], v[28:29]
	v_mov_b32_e32 v30, v25
	v_mul_f32_e32 v2, v28, v29
	v_rcp_f32_e32 v29, v6
	v_mul_f32_e32 v6, 0xbfb8aa3b, v33
	v_exp_f32_e32 v6, v6
	v_mul_f32_e32 v28, v88, v15
	v_and_b32_e32 v7, 0xffff0000, v7
	v_pk_mul_f32 v[24:25], v[28:29], v[30:31]
	v_add_f32_e32 v6, 1.0, v6
	v_mul_f32_e32 v21, v24, v25
	v_rcp_f32_e32 v25, v6
	v_mul_f32_e32 v6, 0xbfb8aa3b, v7
	v_exp_f32_e32 v6, v6
	v_mul_f32_e32 v24, v86, v15
	v_mov_b32_e32 v32, v26
	v_pk_mul_f32 v[24:25], v[24:25], v[32:33]
	v_add_f32_e32 v6, 1.0, v6
	v_mul_f32_e32 v23, v24, v25
	v_rcp_f32_e32 v25, v6
	v_mul_f32_e32 v24, v84, v15
	v_mov_b32_e32 v6, v27
	v_mul_f32_e32 v38, v82, v15
	v_pk_mul_f32 v[6:7], v[24:25], v[6:7]
	s_nop 0
	v_mul_f32_e32 v7, v6, v7
	v_cvt_pk_bf16_f32 v6, v2, v21
	v_cvt_pk_bf16_f32 v7, v23, v7
	global_store_dwordx2 v[4:5], v[6:7], off offset:144
	v_mov_b32_e32 v6, v240
	v_mov_b32_e32 v7, v241
	s_nop 0
	ds_read_b128 v[24:27], v219 offset:320
	v_lshlrev_b32_e32 v29, 16, v6
	v_mul_f32_e32 v2, 0xbfb8aa3b, v29
	v_exp_f32_e32 v2, v2
	v_and_b32_e32 v31, 0xffff0000, v6
	v_mul_f32_e32 v6, 0xbfb8aa3b, v31
	v_exp_f32_e32 v6, v6
	v_add_f32_e32 v2, 1.0, v2
	v_rcp_f32_e32 v39, v2
	s_waitcnt lgkmcnt(0)
	v_mov_b32_e32 v28, v24
	v_lshlrev_b32_e32 v33, 16, v7
	v_add_f32_e32 v6, 1.0, v6
	v_pk_mul_f32 v[28:29], v[38:39], v[28:29]
	v_mov_b32_e32 v30, v25
	v_mul_f32_e32 v2, v28, v29
	v_rcp_f32_e32 v29, v6
	v_mul_f32_e32 v6, 0xbfb8aa3b, v33
	v_exp_f32_e32 v6, v6
	v_mul_f32_e32 v28, v72, v15
	v_and_b32_e32 v7, 0xffff0000, v7
	v_pk_mul_f32 v[24:25], v[28:29], v[30:31]
	v_add_f32_e32 v6, 1.0, v6
	v_mul_f32_e32 v21, v24, v25
	v_rcp_f32_e32 v25, v6
	v_mul_f32_e32 v6, 0xbfb8aa3b, v7
	v_exp_f32_e32 v6, v6
	v_mul_f32_e32 v24, v70, v15
	v_mov_b32_e32 v32, v26
	v_pk_mul_f32 v[24:25], v[24:25], v[32:33]
	v_add_f32_e32 v6, 1.0, v6
	v_mul_f32_e32 v23, v24, v25
	v_rcp_f32_e32 v25, v6
	v_mul_f32_e32 v24, v68, v15
	v_mov_b32_e32 v6, v27
	v_mul_f32_e32 v38, v66, v15
	v_pk_mul_f32 v[6:7], v[24:25], v[6:7]
	s_nop 0
	v_mul_f32_e32 v7, v6, v7
	v_cvt_pk_bf16_f32 v6, v2, v21
	v_cvt_pk_bf16_f32 v7, v23, v7
	global_store_dwordx2 v[4:5], v[6:7], off offset:160
	v_mov_b32_e32 v6, v242
	v_mov_b32_e32 v7, v243
	s_nop 0
	ds_read_b128 v[24:27], v219 offset:352
	v_lshlrev_b32_e32 v29, 16, v6
	v_mul_f32_e32 v2, 0xbfb8aa3b, v29
	v_exp_f32_e32 v2, v2
	v_and_b32_e32 v31, 0xffff0000, v6
	v_mul_f32_e32 v6, 0xbfb8aa3b, v31
	v_exp_f32_e32 v6, v6
	v_add_f32_e32 v2, 1.0, v2
	v_rcp_f32_e32 v39, v2
	s_waitcnt lgkmcnt(0)
	v_mov_b32_e32 v28, v24
	v_lshlrev_b32_e32 v33, 16, v7
	v_add_f32_e32 v6, 1.0, v6
	v_pk_mul_f32 v[28:29], v[38:39], v[28:29]
	v_mov_b32_e32 v30, v25
	v_mul_f32_e32 v2, v28, v29
	v_rcp_f32_e32 v29, v6
	v_mul_f32_e32 v6, 0xbfb8aa3b, v33
	v_exp_f32_e32 v6, v6
	v_mul_f32_e32 v28, v62, v15
	v_and_b32_e32 v7, 0xffff0000, v7
	v_pk_mul_f32 v[24:25], v[28:29], v[30:31]
	v_add_f32_e32 v6, 1.0, v6
	v_mul_f32_e32 v21, v24, v25
	v_rcp_f32_e32 v25, v6
	v_mul_f32_e32 v6, 0xbfb8aa3b, v7
	v_exp_f32_e32 v6, v6
	v_mul_f32_e32 v24, v60, v15
	v_mov_b32_e32 v32, v26
	v_pk_mul_f32 v[24:25], v[24:25], v[32:33]
	v_add_f32_e32 v6, 1.0, v6
	v_mul_f32_e32 v23, v24, v25
	v_rcp_f32_e32 v25, v6
	v_mul_f32_e32 v24, v58, v15
	v_mov_b32_e32 v6, v27
	v_mul_f32_e32 v38, v56, v15
	v_pk_mul_f32 v[6:7], v[24:25], v[6:7]
	s_nop 0
	v_mul_f32_e32 v7, v6, v7
	v_cvt_pk_bf16_f32 v6, v2, v21
	v_cvt_pk_bf16_f32 v7, v23, v7
	global_store_dwordx2 v[4:5], v[6:7], off offset:176
	v_mov_b32_e32 v6, v244
	v_mov_b32_e32 v7, v245
	s_nop 0
	ds_read_b128 v[24:27], v219 offset:384
	v_lshlrev_b32_e32 v29, 16, v6
	v_mul_f32_e32 v2, 0xbfb8aa3b, v29
	v_exp_f32_e32 v2, v2
	v_and_b32_e32 v31, 0xffff0000, v6
	v_mul_f32_e32 v6, 0xbfb8aa3b, v31
	v_exp_f32_e32 v6, v6
	v_add_f32_e32 v2, 1.0, v2
	v_rcp_f32_e32 v39, v2
	s_waitcnt lgkmcnt(0)
; DI u32 cvtpk(float lo, float hi) { u32 r; asm volatile("v_cvt_pk_bf16_f32 %0, %1, %2" : "=v"(r) : "v"(lo), "v"(hi)); return r; }
; DI float silu(float x) { return x * __builtin_amdgcn_rcpf(1.f + __expf(-x)); }
; DI void attn_item(const Params& p, char* smem, u16* qbase, const u16* gabase, const u16* kbase, const u16* vtbase,
;                   int tkv, int nkt, int mylimit, const float* lam_p, const int g_wave) {
;     ...
; #pragma unroll
;     for (int d = 0; d < 4; ++d)
; #pragma unroll
;       for (int g = 0; g < 4; ++g) {
;         int dv = 32 * d + 8 * g + 4 * hh;
;         u32x2 gg = *(const u32x2*)(garow + dv);
;         float4 sl = *(const float4*)(p.subln + dv);
;         float g0 = __uint_as_float(gg[0] << 16), g1 = __uint_as_float(gg[0] & 0xffff0000u), g2 = __uint_as_float(gg[1] << 16), g3 = __uint_as_float(gg[1] & 0xffff0000u);
;         float o0 = O0[d][4 * g + 0] * rs * sl.x * silu(g0);
;         float o1 = O0[d][4 * g + 1] * rs * sl.y * silu(g1);
;         float o2 = O0[d][4 * g + 2] * rs * sl.z * silu(g2);
;         float o3 = O0[d][4 * g + 3] * rs * sl.w * silu(g3);
;         u32x2 o; o[0] = cvtpk(o0, o1); o[1] = cvtpk(o2, o3);
;         *(u32x2*)(qrow + dv) = o;
;       }
	v_mov_b32_e32 v28, v24
	v_lshlrev_b32_e32 v33, 16, v7
	v_add_f32_e32 v6, 1.0, v6
	v_pk_mul_f32 v[28:29], v[38:39], v[28:29]
	v_mov_b32_e32 v30, v25
	v_mul_f32_e32 v2, v28, v29
	v_rcp_f32_e32 v29, v6
	v_mul_f32_e32 v6, 0xbfb8aa3b, v33
	v_exp_f32_e32 v6, v6
	v_mul_f32_e32 v28, v54, v15
	v_and_b32_e32 v7, 0xffff0000, v7
	v_pk_mul_f32 v[24:25], v[28:29], v[30:31]
	v_add_f32_e32 v6, 1.0, v6
	v_mul_f32_e32 v21, v24, v25
	v_rcp_f32_e32 v25, v6
	v_mul_f32_e32 v6, 0xbfb8aa3b, v7
	v_exp_f32_e32 v6, v6
	v_mul_f32_e32 v24, v52, v15
	v_mov_b32_e32 v32, v26
	v_pk_mul_f32 v[24:25], v[24:25], v[32:33]
	v_add_f32_e32 v6, 1.0, v6
	v_mul_f32_e32 v23, v24, v25
	v_rcp_f32_e32 v25, v6
	v_mul_f32_e32 v24, v50, v15
	v_mov_b32_e32 v6, v27
	v_mul_f32_e32 v32, v36, v15
	v_pk_mul_f32 v[6:7], v[24:25], v[6:7]
	s_nop 0
	v_mul_f32_e32 v7, v6, v7
	v_cvt_pk_bf16_f32 v6, v2, v21
	v_cvt_pk_bf16_f32 v7, v23, v7
	global_store_dwordx2 v[4:5], v[6:7], off offset:192
	v_mov_b32_e32 v6, v246
	v_mov_b32_e32 v7, v247
	s_nop 0
	ds_read_b128 v[24:27], v219 offset:416
	v_lshlrev_b32_e32 v29, 16, v6
	v_mul_f32_e32 v2, 0xbfb8aa3b, v29
	v_exp_f32_e32 v2, v2
	v_and_b32_e32 v31, 0xffff0000, v6
	v_mul_f32_e32 v6, 0xbfb8aa3b, v31
	v_exp_f32_e32 v6, v6
	v_add_f32_e32 v2, 1.0, v2
	v_rcp_f32_e32 v33, v2
	s_waitcnt lgkmcnt(0)
	v_mov_b32_e32 v28, v24
	v_lshlrev_b32_e32 v23, 16, v7
	v_add_f32_e32 v6, 1.0, v6
	v_pk_mul_f32 v[28:29], v[32:33], v[28:29]
	v_mov_b32_e32 v30, v25
	v_mul_f32_e32 v2, v28, v29
	v_rcp_f32_e32 v29, v6
	v_mul_f32_e32 v6, 0xbfb8aa3b, v23
	v_exp_f32_e32 v6, v6
	v_mul_f32_e32 v28, v34, v15
	v_and_b32_e32 v7, 0xffff0000, v7
	v_pk_mul_f32 v[24:25], v[28:29], v[30:31]
	v_add_f32_e32 v6, 1.0, v6
	v_mul_f32_e32 v28, v24, v25
	v_rcp_f32_e32 v25, v6
	v_mul_f32_e32 v6, 0xbfb8aa3b, v7
	v_exp_f32_e32 v6, v6
	v_mul_f32_e32 v24, v22, v15
	v_mov_b32_e32 v22, v26
	v_pk_mul_f32 v[22:23], v[24:25], v[22:23]
	v_add_f32_e32 v6, 1.0, v6
	v_rcp_f32_e32 v21, v6
	v_mov_b32_e32 v6, v27
	v_mul_f32_e32 v22, v22, v23
	v_mul_f32_e32 v30, v16, v15
	v_pk_mul_f32 v[6:7], v[20:21], v[6:7]
	s_nop 0
	v_mul_f32_e32 v7, v6, v7
	v_cvt_pk_bf16_f32 v6, v2, v28
	v_cvt_pk_bf16_f32 v7, v22, v7
	global_store_dwordx2 v[4:5], v[6:7], off offset:208
	v_mov_b32_e32 v6, v248
	v_mov_b32_e32 v7, v249
	s_nop 0
	ds_read_b128 v[20:23], v219 offset:448
	v_lshlrev_b32_e32 v25, 16, v6
	v_mul_f32_e32 v2, 0xbfb8aa3b, v25
	v_exp_f32_e32 v2, v2
	v_and_b32_e32 v27, 0xffff0000, v6
	v_mul_f32_e32 v6, 0xbfb8aa3b, v27
	v_exp_f32_e32 v6, v6
	v_add_f32_e32 v2, 1.0, v2
	v_rcp_f32_e32 v31, v2
	s_waitcnt lgkmcnt(0)
	v_mov_b32_e32 v24, v20
	v_lshlrev_b32_e32 v29, 16, v7
	v_add_f32_e32 v6, 1.0, v6
	v_pk_mul_f32 v[24:25], v[30:31], v[24:25]
	v_mov_b32_e32 v26, v21
	v_mul_f32_e32 v2, v24, v25
	v_rcp_f32_e32 v25, v6
	v_mul_f32_e32 v6, 0xbfb8aa3b, v29
	v_exp_f32_e32 v6, v6
	v_mul_f32_e32 v24, v14, v15
	v_and_b32_e32 v7, 0xffff0000, v7
	v_pk_mul_f32 v[20:21], v[24:25], v[26:27]
	v_add_f32_e32 v6, 1.0, v6
	v_mul_f32_e32 v14, v20, v21
	v_rcp_f32_e32 v21, v6
	v_mul_f32_e32 v6, 0xbfb8aa3b, v7
	v_exp_f32_e32 v6, v6
	v_mul_f32_e32 v20, v13, v15
	v_mov_b32_e32 v28, v22
	v_pk_mul_f32 v[20:21], v[20:21], v[28:29]
	v_add_f32_e32 v6, 1.0, v6
	v_rcp_f32_e32 v13, v6
	v_mov_b32_e32 v6, v23
	v_mul_f32_e32 v16, v20, v21
	v_mul_f32_e32 v24, v11, v15
	v_pk_mul_f32 v[6:7], v[12:13], v[6:7]
	s_nop 0
	v_mul_f32_e32 v7, v6, v7
	v_cvt_pk_bf16_f32 v6, v2, v14
	v_cvt_pk_bf16_f32 v7, v16, v7
	global_store_dwordx2 v[4:5], v[6:7], off offset:224
	v_mov_b32_e32 v6, v250
	v_mov_b32_e32 v7, v251
	s_nop 0
	ds_read_b128 v[16:19], v219 offset:480
	v_and_b32_e32 v21, 0xffff0000, v6
	v_lshlrev_b32_e32 v13, 16, v6
	v_mul_f32_e32 v6, 0xbfb8aa3b, v21
	v_mul_f32_e32 v2, 0xbfb8aa3b, v13
	v_exp_f32_e32 v6, v6
	v_exp_f32_e32 v2, v2
	v_lshlrev_b32_e32 v23, 16, v7
	s_waitcnt lgkmcnt(0)
	v_mov_b32_e32 v12, v16
	v_add_f32_e32 v6, 1.0, v6
	v_add_f32_e32 v2, 1.0, v2
	v_rcp_f32_e32 v11, v6
	v_mul_f32_e32 v6, 0xbfb8aa3b, v23
	v_rcp_f32_e32 v25, v2
	v_exp_f32_e32 v6, v6
	v_mov_b32_e32 v20, v17
	v_and_b32_e32 v7, 0xffff0000, v7
	v_pk_mul_f32 v[12:13], v[24:25], v[12:13]
	v_pk_mul_f32 v[10:11], v[10:11], v[20:21]
	v_add_f32_e32 v6, 1.0, v6
	v_mul_f32_e32 v2, v12, v13
	v_mul_f32_e32 v12, v10, v11
	v_rcp_f32_e32 v11, v6
	v_mul_f32_e32 v6, 0xbfb8aa3b, v7
	v_exp_f32_e32 v6, v6
	v_mul_f32_e32 v10, v9, v15
	v_mov_b32_e32 v22, v18
	v_pk_mul_f32 v[10:11], v[10:11], v[22:23]
	v_add_f32_e32 v6, 1.0, v6
	v_rcp_f32_e32 v9, v6
	v_mov_b32_e32 v6, v19
	v_mul_f32_e32 v10, v10, v11
	v_pk_mul_f32 v[6:7], v[8:9], v[6:7]
	s_nop 0
	v_mul_f32_e32 v7, v6, v7
	v_cvt_pk_bf16_f32 v6, v2, v12
	v_cvt_pk_bf16_f32 v7, v10, v7
	global_store_dwordx2 v[4:5], v[6:7], off offset:240
